# attention: 6-8 of the 16 end-of-tile exps (those whose destinations are free) moved into PV group-2 MFMA gaps, on top of v31
# speedup vs baseline: 1.0131x; 1.0053x over previous
; #define SLOAD(i, k0) do { sr_[i].vs0 = ld8(&Vh[(long)((k0) + sr) * LDK + sc]); sr_[i].vs1 = ld8(&Vh[(long)((k0) + 32 + sr) * LDK + sc]); \
;     sr_[i].ks0 = ld8(&Kh[(long)((k0) + sr) * LDK + sc]); sr_[i].ks1 = ld8(&Kh[(long)((k0) + 32 + sr) * LDK + sc]); } while (0)
; #define SWAIT() asm volatile("s_waitcnt vmcnt(4)" ::: "memory")
; #define SWRITE_I(B, i) do { LDSV(wv0 + (B) * 16384) = sr_[i].vs0; LDSV(wv1 + (B) * 16384) = sr_[i].vs1; LDSV(wk0 + (B) * 16384) = sr_[i].ks0; LDSV(wk1 + (B) * 16384) = sr_[i].ks1; } while (0)
; #define NOP_() do { } while (0)
; __device__ __forceinline__ void finishSM(f32x16& p0, f32x16& p1, float alpha, float& l_reg, bf16x8& pa0, bf16x8& pa1, bf16x8& pa2, bf16x8& pa3) {
;   for (int r = 0; r < 16; ++r) p1[r] = __builtin_amdgcn_exp2f(p1[r]);
;   float ps = 0; for (int r = 0; r < 16; ++r) ps += p0[r]; for (int r = 0; r < 16; ++r) ps += p1[r];
;   { auto rr = __builtin_amdgcn_permlane32_swap(__float_as_uint(ps), __float_as_uint(ps), false, false);
;     ps = __uint_as_float(rr[0]) + __uint_as_float(rr[1]); }
;   l_reg = l_reg * alpha + ps;
;     ...
;   PK4(p0, 0, pa0); PK4(p0, 8, pa1); PK4(p1, 0, pa2); PK4(p1, 8, pa3);
;     ...
; }
; template <bool PARTIAL, bool FIXED> ...
;     ...
;   int j = 1;
;   for (; j + 6 < NT; j += 6) {
;     HALF_B(1, 0, SLOAD(1, (j + 2) * KVBLK), do { SWAIT(); SWRITE_I(2, 0); } while (0));
;     HALF_A(2, 1, NOP_(), SLOAD(0, (j + 3) * KVBLK), do { SWAIT(); SWRITE_I(0, 1); } while (0));
;     HALF_B(0, 2, SLOAD(1, (j + 4) * KVBLK), do { SWAIT(); SWRITE_I(1, 0); } while (0));
;     HALF_A(1, 0, NOP_(), SLOAD(0, (j + 5) * KVBLK), do { SWAIT(); SWRITE_I(2, 1); } while (0));
;     HALF_B(2, 1, SLOAD(1, (j + 6) * KVBLK), do { SWAIT(); SWRITE_I(0, 0); } while (0));
;     HALF_A(0, 2, NOP_(), SLOAD(0, (j + 7) * KVBLK), do { SWAIT(); SWRITE_I(1, 1); } while (0));
.LBB0_352:
	s_waitcnt lgkmcnt(0)
	s_barrier
	ds_read_b128 v[80:83], v207 offset:16384
	ds_read_b128 v[84:87], v207 offset:24576
	ds_read_b128 v[162:165], v208 offset:16384
	ds_read_b128 v[166:169], v208 offset:24576
	v_exp_f32_e32 v170, v72
	v_exp_f32_e32 v171, v73
	v_exp_f32_e32 v172, v74
	v_exp_f32_e32 v173, v75
	v_exp_f32_e32 v174, v76
	v_exp_f32_e32 v175, v77
	v_exp_f32_e32 v176, v78
	v_exp_f32_e32 v79, v79
	s_waitcnt lgkmcnt(3)
	v_mfma_f32_32x32x16_bf16 v[96:111], v[80:83], v[142:145], 0
	v_exp_f32_e32 v236, v64
	v_add_f32_e32 v64, 0, v229
	v_add_f32_e32 v64, v243, v64
	v_add_f32_e32 v64, v244, v64
	s_waitcnt lgkmcnt(2)
	v_mfma_f32_32x32x16_bf16 v[80:95], v[84:87], v[142:145], 0
	v_add_f32_e32 v64, v246, v64
	v_add_f32_e32 v64, v242, v64
	v_add_f32_e32 v64, v245, v64
	s_waitcnt lgkmcnt(1)
	v_mfma_f32_32x32x16_bf16 v[96:111], v[162:165], v[138:141], v[96:111]
	v_add_f32_e32 v64, v227, v64
	v_add_f32_e32 v64, v228, v64
	v_add_f32_e32 v64, v223, v64
	s_waitcnt lgkmcnt(0)
	v_mfma_f32_32x32x16_bf16 v[80:95], v[166:169], v[138:141], v[80:95]
	ds_read_b128 v[162:165], v209 offset:16384
	ds_read_b128 v[166:169], v209 offset:24576
	v_add_f32_e32 v64, v226, v64
	v_add_f32_e32 v64, v224, v64
	v_add_f32_e32 v64, v225, v64
	v_add_f32_e32 v64, v220, v64
	v_exp_f32_e32 v237, v65
	s_waitcnt lgkmcnt(1)
	v_mfma_f32_32x32x16_bf16 v[96:111], v[162:165], v[112:115], v[96:111]
	v_add_f32_e32 v64, v222, v64
	v_exp_f32_e32 v238, v66
	v_add_f32_e32 v64, v219, v64
	v_exp_f32_e32 v239, v67
	s_waitcnt lgkmcnt(0)
	v_mfma_f32_32x32x16_bf16 v[80:95], v[166:169], v[112:115], v[80:95]
	ds_read_b128 v[162:165], v210 offset:16384
	ds_read_b128 v[166:169], v210 offset:24576
	v_add_f32_e32 v64, v221, v64
	v_exp_f32_e32 v247, v68
	v_add_f32_e32 v64, v236, v64
	v_exp_f32_e32 v248, v69
	s_waitcnt lgkmcnt(1)
	v_mfma_f32_32x32x16_bf16 v[96:111], v[162:165], v[116:119], v[96:111]
	v_add_f32_e32 v64, v237, v64
	v_exp_f32_e32 v249, v70
	v_add_f32_e32 v64, v238, v64
	v_exp_f32_e32 v252, v71
	s_waitcnt lgkmcnt(0)
	v_mfma_f32_32x32x16_bf16 v[80:95], v[166:169], v[116:119], v[80:95]
	ds_read_b128 v[162:165], v190 offset:16384
	ds_read_b128 v[166:169], v190 offset:24576
	v_add_f32_e32 v64, v239, v64
	v_add_f32_e32 v64, v247, v64
	v_add_f32_e32 v64, v248, v64
	v_add_f32_e32 v64, v249, v64
	v_add_f32_e32 v64, v252, v64
	v_add_f32_e32 v64, v170, v64
	s_waitcnt lgkmcnt(1)
	v_mfma_f32_32x32x16_bf16 v[96:111], v[162:165], v[120:123], v[96:111]
	v_add_f32_e32 v64, v171, v64
	v_add_f32_e32 v64, v172, v64
	v_add_f32_e32 v64, v173, v64
	v_add_f32_e32 v64, v174, v64
	v_add_f32_e32 v64, v175, v64
	s_waitcnt lgkmcnt(0)
	v_mfma_f32_32x32x16_bf16 v[80:95], v[166:169], v[120:123], v[80:95]
	ds_read_b128 v[162:165], v191 offset:16384
	ds_read_b128 v[166:169], v191 offset:24576
	v_add_f32_e32 v64, v176, v64
	v_add_f32_e32 v64, v79, v64
	v_mov_b32_e32 v65, v64
	s_nop 1
	v_permlane32_swap_b32_e32 v64, v65
	v_add_f32_e32 v64, v64, v65
	s_waitcnt lgkmcnt(1)
	v_mfma_f32_32x32x16_bf16 v[96:111], v[162:165], v[124:127], v[96:111]
	v_add_f32_e32 v128, v215, v64
	v_cvt_pk_bf16_f32 v64, v229, v243
	v_cvt_pk_bf16_f32 v65, v244, v246
	v_cvt_pk_bf16_f32 v66, v242, v245
	v_cvt_pk_bf16_f32 v67, v227, v228
	s_waitcnt lgkmcnt(0)
	v_mfma_f32_32x32x16_bf16 v[80:95], v[166:169], v[124:127], v[80:95]
	ds_read_b128 v[162:165], v192 offset:16384
	ds_read_b128 v[166:169], v192 offset:24576
	v_cvt_pk_bf16_f32 v68, v223, v226
	v_cvt_pk_bf16_f32 v69, v224, v225
	v_cvt_pk_bf16_f32 v70, v220, v222
	v_cvt_pk_bf16_f32 v71, v219, v221
	v_cvt_pk_bf16_f32 v72, v236, v237
	v_cvt_pk_bf16_f32 v73, v238, v239
	s_waitcnt lgkmcnt(1)
	v_mfma_f32_32x32x16_bf16 v[96:111], v[162:165], v[130:133], v[96:111]
	v_cvt_pk_bf16_f32 v74, v247, v248
	v_cvt_pk_bf16_f32 v75, v249, v252
	v_cvt_pk_bf16_f32 v76, v170, v171
	v_cvt_pk_bf16_f32 v77, v172, v173
	v_cvt_pk_bf16_f32 v78, v174, v175
	s_waitcnt lgkmcnt(0)
	v_mfma_f32_32x32x16_bf16 v[80:95], v[166:169], v[130:133], v[80:95]
	ds_read_b128 v[162:165], v193 offset:16384
	ds_read_b128 v[166:169], v193 offset:24576
	ds_read_b64_tr_b16 v[180:181], v206 offset:0
	ds_read_b64_tr_b16 v[182:183], v206 offset:0x800
	ds_read_b64_tr_b16 v[184:185], v206 offset:0x1000
	ds_read_b64_tr_b16 v[186:187], v206 offset:0x1800
	ds_read_b64_tr_b16 v[216:217], v206 offset:0x2000
	ds_read_b64_tr_b16 v[218:219], v206 offset:0x2800
	ds_read_b64_tr_b16 v[220:221], v206 offset:0x3000
	ds_read_b64_tr_b16 v[222:223], v206 offset:0x3800
	v_cvt_pk_bf16_f32 v79, v176, v79
	s_nop 0
	v_permlane32_swap_b32_e32 v64, v66
	v_permlane32_swap_b32_e32 v65, v67
	v_permlane32_swap_b32_e32 v68, v70
	v_permlane32_swap_b32_e32 v69, v71
	s_waitcnt lgkmcnt(9)
	v_mfma_f32_32x32x16_bf16 v[96:111], v[162:165], v[134:137], v[96:111]
	v_permlane32_swap_b32_e32 v72, v74
	v_permlane32_swap_b32_e32 v73, v75
	v_permlane32_swap_b32_e32 v76, v78
	v_permlane32_swap_b32_e32 v77, v79
	s_waitcnt lgkmcnt(8)
	v_mfma_f32_32x32x16_bf16 v[80:95], v[166:169], v[134:137], v[80:95]
	s_waitcnt vmcnt(0)
	ds_write_b128 v211, v[146:149] offset:32768
	s_nop 0
	s_waitcnt lgkmcnt(7)
	v_mfma_f32_32x32x16_bf16 v[0:15], v[64:67], v[180:183], v[0:15]
	ds_read_b64_tr_b16 v[180:181], v206 offset:0x200
	ds_read_b64_tr_b16 v[182:183], v206 offset:0xa00
	v_add_co_u32_e32 v166, vcc, s19, v178
	s_nop 1
	v_addc_co_u32_e32 v167, vcc, -1, v179, vcc
	v_add_co_u32_e32 v170, vcc, s20, v178
	s_nop 1
	v_addc_co_u32_e32 v171, vcc, -1, v179, vcc
	s_waitcnt lgkmcnt(7)
	v_mfma_f32_32x32x16_bf16 v[0:15], v[68:71], v[184:187], v[0:15]
	ds_read_b64_tr_b16 v[184:185], v206 offset:0x1200
	ds_read_b64_tr_b16 v[186:187], v206 offset:0x1a00
	global_load_dwordx4 v[162:165], v[166:167], off
	s_nop 0
	global_load_dwordx4 v[166:169], v[166:167], off offset:-512
	s_nop 0
	global_load_dwordx4 v[174:177], v[170:171], off
	s_nop 0
	global_load_dwordx4 v[170:173], v[170:171], off offset:-512
	s_waitcnt lgkmcnt(7)
; #define SBAR() __builtin_amdgcn_sched_barrier(0)
; __device__ __forceinline__ void partialSM_fixed(f32x16& p0) {
;   for (int r = 0; r < 16; ++r) p0[r] = __builtin_amdgcn_exp2f(p0[r]);
; }
; template <int D0, int BOFF> __device__ __forceinline__ void pv_one_i(f32x16& od, int vb, bf16x8 pa0, bf16x8 pa1, bf16x8 pa2, bf16x8 pa3) {
;   const s16x4 l0 = tr_read<BOFF + v_rd_off(D0, 0, 0)>(vb), h0 = tr_read<BOFF + v_rd_off(D0, 0, 1)>(vb), l1 = tr_read<BOFF + v_rd_off(D0, 1, 0)>(vb), h1 = tr_read<BOFF + v_rd_off(D0, 1, 1)>(vb);
;   const s16x4 l2 = tr_read<BOFF + v_rd_off(D0, 2, 0)>(vb), h2 = tr_read<BOFF + v_rd_off(D0, 2, 1)>(vb), l3 = tr_read<BOFF + v_rd_off(D0, 3, 0)>(vb), h3 = tr_read<BOFF + v_rd_off(D0, 3, 1)>(vb);
;   asm volatile("s_waitcnt lgkmcnt(0)" ::: "memory"); SBAR();
;     ...
;   od = __builtin_amdgcn_mfma_f32_32x32x16_bf16(pa0, PK(l0, h0), od, 0, 0, 0);
;   od = __builtin_amdgcn_mfma_f32_32x32x16_bf16(pa1, PK(l1, h1), od, 0, 0, 0);
;   od = __builtin_amdgcn_mfma_f32_32x32x16_bf16(pa2, PK(l2, h2), od, 0, 0, 0);
;   od = __builtin_amdgcn_mfma_f32_32x32x16_bf16(pa3, PK(l3, h3), od, 0, 0, 0);
;     ...
; }
; template <int BOFF> __device__ __forceinline__ void pv_i(f32x16* o, int vb, bf16x8 pa0, bf16x8 pa1, bf16x8 pa2, bf16x8 pa3) {
;   pv_one_i<0, BOFF>(o[0], vb, pa0, pa1, pa2, pa3); pv_one_i<1, BOFF>(o[1], vb, pa0, pa1, pa2, pa3); pv_one_i<2, BOFF>(o[2], vb, pa0, pa1, pa2, pa3); pv_one_i<3, BOFF>(o[3], vb, pa0, pa1, pa2, pa3);
; }
	v_mfma_f32_32x32x16_bf16 v[0:15], v[72:75], v[216:219], v[0:15]
	ds_read_b64_tr_b16 v[216:217], v206 offset:0x2200
	ds_read_b64_tr_b16 v[218:219], v206 offset:0x2a00
	s_waitcnt lgkmcnt(7)
	v_mfma_f32_32x32x16_bf16 v[0:15], v[76:79], v[220:223], v[0:15]
	ds_read_b64_tr_b16 v[220:221], v206 offset:0x3200
	ds_read_b64_tr_b16 v[222:223], v206 offset:0x3a00
	ds_write_b128 v212, v[150:153] offset:32768
	s_waitcnt lgkmcnt(7)
	v_mfma_f32_32x32x16_bf16 v[16:31], v[64:67], v[180:183], v[16:31]
	ds_read_b64_tr_b16 v[180:181], v206 offset:0x400
	ds_read_b64_tr_b16 v[182:183], v206 offset:0xc00
	s_waitcnt lgkmcnt(7)
	v_mfma_f32_32x32x16_bf16 v[16:31], v[68:71], v[184:187], v[16:31]
	ds_read_b64_tr_b16 v[184:185], v206 offset:0x1400
	ds_read_b64_tr_b16 v[186:187], v206 offset:0x1c00
	s_waitcnt lgkmcnt(7)
	v_mfma_f32_32x32x16_bf16 v[16:31], v[72:75], v[216:219], v[16:31]
	ds_read_b64_tr_b16 v[216:217], v206 offset:0x2400
	ds_read_b64_tr_b16 v[218:219], v206 offset:0x2c00
	s_waitcnt lgkmcnt(7)
	v_mfma_f32_32x32x16_bf16 v[16:31], v[76:79], v[220:223], v[16:31]
	ds_read_b64_tr_b16 v[220:221], v206 offset:0x3400
	ds_read_b64_tr_b16 v[222:223], v206 offset:0x3c00
	ds_write_b128 v213, v[154:157] offset:32768
	s_waitcnt lgkmcnt(7)
	v_mfma_f32_32x32x16_bf16 v[32:47], v[64:67], v[180:183], v[32:47]
	ds_read_b64_tr_b16 v[180:181], v206 offset:0x600
	ds_read_b64_tr_b16 v[182:183], v206 offset:0xe00
	v_exp_f32_e32 v215, v108
	v_exp_f32_e32 v188, v102
	s_waitcnt lgkmcnt(7)
	v_mfma_f32_32x32x16_bf16 v[32:47], v[68:71], v[184:187], v[32:47]
	ds_read_b64_tr_b16 v[184:185], v206 offset:0x1600
	ds_read_b64_tr_b16 v[186:187], v206 offset:0x1e00
	v_exp_f32_e32 v189, v103
	v_exp_f32_e32 v196, v104
	s_waitcnt lgkmcnt(7)
	v_mfma_f32_32x32x16_bf16 v[32:47], v[72:75], v[216:219], v[32:47]
	ds_read_b64_tr_b16 v[216:217], v206 offset:0x2600
	ds_read_b64_tr_b16 v[218:219], v206 offset:0x2e00
	v_exp_f32_e32 v197, v105
	v_exp_f32_e32 v198, v106
	s_waitcnt lgkmcnt(7)
	v_mfma_f32_32x32x16_bf16 v[32:47], v[76:79], v[220:223], v[32:47]
	ds_read_b64_tr_b16 v[220:221], v206 offset:0x3600
	ds_read_b64_tr_b16 v[222:223], v206 offset:0x3e00
	v_exp_f32_e32 v199, v107
	ds_write_b128 v214, v[158:161] offset:32768
	s_waitcnt lgkmcnt(7)
	v_mfma_f32_32x32x16_bf16 v[48:63], v[64:67], v[180:183], v[48:63]
	s_waitcnt vmcnt(4)
	v_exp_f32_e32 v181, v96
	v_exp_f32_e32 v183, v97
	s_waitcnt lgkmcnt(5)
	v_mfma_f32_32x32x16_bf16 v[48:63], v[68:71], v[184:187], v[48:63]
	v_exp_f32_e32 v184, v98
	v_exp_f32_e32 v185, v99
	v_exp_f32_e32 v186, v100
	v_exp_f32_e32 v187, v101
	s_waitcnt lgkmcnt(3)
	v_mfma_f32_32x32x16_bf16 v[48:63], v[72:75], v[216:219], v[48:63]
	v_exp_f32_e32 v216, v109
	v_exp_f32_e32 v217, v110
	v_exp_f32_e32 v218, v111
	s_waitcnt lgkmcnt(0)
	s_barrier
	v_mfma_f32_32x32x16_bf16 v[48:63], v[76:79], v[220:223], v[48:63]
	ds_read_b128 v[64:67], v207 offset:32768
	ds_read_b128 v[96:99], v207 offset:40960
	ds_read_b128 v[146:149], v208 offset:32768
	ds_read_b128 v[150:153], v208 offset:40960
	v_exp_f32_e32 v154, v88
	v_exp_f32_e32 v155, v89
	v_exp_f32_e32 v156, v90
	v_exp_f32_e32 v157, v91
	v_exp_f32_e32 v158, v92
	v_exp_f32_e32 v159, v93
	v_exp_f32_e32 v160, v94
	v_exp_f32_e32 v95, v95
	s_waitcnt lgkmcnt(3)
	v_mfma_f32_32x32x16_bf16 v[64:79], v[64:67], v[142:145], 0
	v_exp_f32_e32 v236, v80
	v_add_f32_e32 v80, 0, v181
	v_add_f32_e32 v80, v183, v80
	v_add_f32_e32 v80, v184, v80
	s_waitcnt lgkmcnt(2)
	v_mfma_f32_32x32x16_bf16 v[96:111], v[96:99], v[142:145], 0
	v_add_f32_e32 v80, v185, v80
	v_add_f32_e32 v80, v186, v80
	v_add_f32_e32 v80, v187, v80
	s_waitcnt lgkmcnt(1)
	v_mfma_f32_32x32x16_bf16 v[64:79], v[146:149], v[138:141], v[64:79]
	v_add_f32_e32 v80, v188, v80
	v_add_f32_e32 v80, v189, v80
	v_add_f32_e32 v80, v196, v80
	s_waitcnt lgkmcnt(0)
	v_mfma_f32_32x32x16_bf16 v[96:111], v[150:153], v[138:141], v[96:111]
	ds_read_b128 v[146:149], v209 offset:32768
	ds_read_b128 v[150:153], v209 offset:40960
	v_add_f32_e32 v80, v197, v80
	v_add_f32_e32 v80, v198, v80
	v_add_f32_e32 v80, v199, v80
	v_add_f32_e32 v80, v215, v80
	v_exp_f32_e32 v237, v81
	s_waitcnt lgkmcnt(1)
	v_mfma_f32_32x32x16_bf16 v[64:79], v[146:149], v[112:115], v[64:79]
	v_add_f32_e32 v80, v216, v80
	v_exp_f32_e32 v238, v82
	v_add_f32_e32 v80, v217, v80
	v_exp_f32_e32 v239, v83
	s_waitcnt lgkmcnt(0)
	v_mfma_f32_32x32x16_bf16 v[96:111], v[150:153], v[112:115], v[96:111]
	ds_read_b128 v[146:149], v210 offset:32768
	ds_read_b128 v[150:153], v210 offset:40960
	v_add_f32_e32 v80, v218, v80
	v_exp_f32_e32 v247, v84
	v_add_f32_e32 v80, v236, v80
	v_exp_f32_e32 v248, v85
	s_waitcnt lgkmcnt(1)
	v_mfma_f32_32x32x16_bf16 v[64:79], v[146:149], v[116:119], v[64:79]
	v_add_f32_e32 v80, v237, v80
	v_exp_f32_e32 v249, v86
	v_add_f32_e32 v80, v238, v80
	v_exp_f32_e32 v252, v87
	s_waitcnt lgkmcnt(0)
	v_mfma_f32_32x32x16_bf16 v[96:111], v[150:153], v[116:119], v[96:111]
	ds_read_b128 v[146:149], v190 offset:32768
	ds_read_b128 v[150:153], v190 offset:40960
	v_add_f32_e32 v80, v239, v80
	v_add_f32_e32 v80, v247, v80
	v_add_f32_e32 v80, v248, v80
	v_add_f32_e32 v80, v249, v80
	v_add_f32_e32 v80, v252, v80
	v_add_f32_e32 v80, v154, v80
	s_waitcnt lgkmcnt(1)
	v_mfma_f32_32x32x16_bf16 v[64:79], v[146:149], v[120:123], v[64:79]
	v_add_f32_e32 v80, v155, v80
	v_add_f32_e32 v80, v156, v80
	v_add_f32_e32 v80, v157, v80
	v_add_f32_e32 v80, v158, v80
	v_add_f32_e32 v80, v159, v80
	s_waitcnt lgkmcnt(0)
	v_mfma_f32_32x32x16_bf16 v[96:111], v[150:153], v[120:123], v[96:111]
	ds_read_b128 v[146:149], v191 offset:32768
	ds_read_b128 v[150:153], v191 offset:40960
	v_add_f32_e32 v80, v160, v80
	v_add_f32_e32 v180, v95, v80
	v_mov_b32_e32 v182, v180
	v_cvt_pk_bf16_f32 v80, v181, v183
	v_cvt_pk_bf16_f32 v81, v184, v185
	v_cvt_pk_bf16_f32 v82, v186, v187
	s_waitcnt lgkmcnt(1)
; #define SBAR() __builtin_amdgcn_sched_barrier(0)
; __device__ __forceinline__ void partialSM_fixed(f32x16& p0) {
;   for (int r = 0; r < 16; ++r) p0[r] = __builtin_amdgcn_exp2f(p0[r]);
; }
; template <int D0, int BOFF> __device__ __forceinline__ void pv_one_i(f32x16& od, int vb, bf16x8 pa0, bf16x8 pa1, bf16x8 pa2, bf16x8 pa3) {
;   const s16x4 l0 = tr_read<BOFF + v_rd_off(D0, 0, 0)>(vb), h0 = tr_read<BOFF + v_rd_off(D0, 0, 1)>(vb), l1 = tr_read<BOFF + v_rd_off(D0, 1, 0)>(vb), h1 = tr_read<BOFF + v_rd_off(D0, 1, 1)>(vb);
;   const s16x4 l2 = tr_read<BOFF + v_rd_off(D0, 2, 0)>(vb), h2 = tr_read<BOFF + v_rd_off(D0, 2, 1)>(vb), l3 = tr_read<BOFF + v_rd_off(D0, 3, 0)>(vb), h3 = tr_read<BOFF + v_rd_off(D0, 3, 1)>(vb);
;   asm volatile("s_waitcnt lgkmcnt(0)" ::: "memory"); SBAR();
;     ...
;   od = __builtin_amdgcn_mfma_f32_32x32x16_bf16(pa0, PK(l0, h0), od, 0, 0, 0);
;   od = __builtin_amdgcn_mfma_f32_32x32x16_bf16(pa1, PK(l1, h1), od, 0, 0, 0);
;   od = __builtin_amdgcn_mfma_f32_32x32x16_bf16(pa2, PK(l2, h2), od, 0, 0, 0);
;   od = __builtin_amdgcn_mfma_f32_32x32x16_bf16(pa3, PK(l3, h3), od, 0, 0, 0);
;     ...
; }
; template <int BOFF> __device__ __forceinline__ void pv_i(f32x16* o, int vb, bf16x8 pa0, bf16x8 pa1, bf16x8 pa2, bf16x8 pa3) {
;   pv_one_i<0, BOFF>(o[0], vb, pa0, pa1, pa2, pa3); pv_one_i<1, BOFF>(o[1], vb, pa0, pa1, pa2, pa3); pv_one_i<2, BOFF>(o[2], vb, pa0, pa1, pa2, pa3); pv_one_i<3, BOFF>(o[3], vb, pa0, pa1, pa2, pa3);
; }
	v_mfma_f32_32x32x16_bf16 v[64:79], v[146:149], v[124:127], v[64:79]
	v_cvt_pk_bf16_f32 v83, v188, v189
	v_cvt_pk_bf16_f32 v84, v196, v197
	v_cvt_pk_bf16_f32 v85, v198, v199
	v_cvt_pk_bf16_f32 v86, v215, v216
	v_cvt_pk_bf16_f32 v87, v217, v218
	s_waitcnt lgkmcnt(0)
	v_mfma_f32_32x32x16_bf16 v[96:111], v[150:153], v[124:127], v[96:111]
	ds_read_b128 v[146:149], v192 offset:32768
	ds_read_b128 v[150:153], v192 offset:40960
	v_cvt_pk_bf16_f32 v88, v236, v237
	v_cvt_pk_bf16_f32 v89, v238, v239
	v_cvt_pk_bf16_f32 v90, v247, v248
	v_cvt_pk_bf16_f32 v91, v249, v252
	v_cvt_pk_bf16_f32 v92, v154, v155
	v_cvt_pk_bf16_f32 v93, v156, v157
	s_waitcnt lgkmcnt(1)
	v_mfma_f32_32x32x16_bf16 v[64:79], v[146:149], v[130:133], v[64:79]
	v_cvt_pk_bf16_f32 v94, v158, v159
	v_cvt_pk_bf16_f32 v95, v160, v95
	s_nop 1
	v_permlane32_swap_b32_e32 v180, v182
	v_permlane32_swap_b32_e32 v80, v82
	s_waitcnt lgkmcnt(0)
	v_mfma_f32_32x32x16_bf16 v[96:111], v[150:153], v[130:133], v[96:111]
	ds_read_b128 v[146:149], v193 offset:32768
	ds_read_b128 v[150:153], v193 offset:40960
	ds_read_b64_tr_b16 v[184:185], v206 offset:0x4000
	ds_read_b64_tr_b16 v[186:187], v206 offset:0x4800
	ds_read_b64_tr_b16 v[216:217], v206 offset:0x5000
	ds_read_b64_tr_b16 v[218:219], v206 offset:0x5800
	ds_read_b64_tr_b16 v[220:221], v206 offset:0x6000
	ds_read_b64_tr_b16 v[222:223], v206 offset:0x6800
	ds_read_b64_tr_b16 v[224:225], v206 offset:0x7000
	ds_read_b64_tr_b16 v[226:227], v206 offset:0x7800
	v_permlane32_swap_b32_e32 v81, v83
	v_permlane32_swap_b32_e32 v84, v86
	v_permlane32_swap_b32_e32 v85, v87
	v_permlane32_swap_b32_e32 v88, v90
	v_permlane32_swap_b32_e32 v89, v91
	v_permlane32_swap_b32_e32 v92, v94
	s_waitcnt lgkmcnt(9)
	v_mfma_f32_32x32x16_bf16 v[64:79], v[146:149], v[134:137], v[64:79]
	v_permlane32_swap_b32_e32 v93, v95
	s_waitcnt lgkmcnt(8)
	v_mfma_f32_32x32x16_bf16 v[96:111], v[150:153], v[134:137], v[96:111]
	s_waitcnt vmcnt(0)
	ds_write_b128 v211, v[162:165]
	s_nop 0
	s_waitcnt lgkmcnt(7)
	v_mfma_f32_32x32x16_bf16 v[0:15], v[80:83], v[184:187], v[0:15]
	ds_read_b64_tr_b16 v[184:185], v206 offset:0x4200
	ds_read_b64_tr_b16 v[186:187], v206 offset:0x4a00
	v_add_co_u32_e32 v150, vcc, s21, v178
	s_nop 1
	v_addc_co_u32_e32 v151, vcc, -1, v179, vcc
	v_add_co_u32_e32 v154, vcc, s22, v178
	s_nop 1
	v_addc_co_u32_e32 v155, vcc, -1, v179, vcc
	s_waitcnt lgkmcnt(7)
	v_mfma_f32_32x32x16_bf16 v[0:15], v[84:87], v[216:219], v[0:15]
	ds_read_b64_tr_b16 v[216:217], v206 offset:0x5200
	ds_read_b64_tr_b16 v[218:219], v206 offset:0x5a00
	global_load_dwordx4 v[146:149], v[150:151], off
	s_nop 0
	global_load_dwordx4 v[150:153], v[150:151], off offset:-512
	s_nop 0
	global_load_dwordx4 v[158:161], v[154:155], off
	s_nop 0
	global_load_dwordx4 v[154:157], v[154:155], off offset:-512
	s_waitcnt lgkmcnt(7)
	v_mfma_f32_32x32x16_bf16 v[0:15], v[88:91], v[220:223], v[0:15]
	ds_read_b64_tr_b16 v[220:221], v206 offset:0x6200
	ds_read_b64_tr_b16 v[222:223], v206 offset:0x6a00
	s_waitcnt lgkmcnt(7)
	v_mfma_f32_32x32x16_bf16 v[0:15], v[92:95], v[224:227], v[0:15]
	ds_read_b64_tr_b16 v[224:225], v206 offset:0x7200
	ds_read_b64_tr_b16 v[226:227], v206 offset:0x7a00
	ds_write_b128 v212, v[174:177]
	s_waitcnt lgkmcnt(7)
	v_mfma_f32_32x32x16_bf16 v[16:31], v[80:83], v[184:187], v[16:31]
	ds_read_b64_tr_b16 v[184:185], v206 offset:0x4400
	ds_read_b64_tr_b16 v[186:187], v206 offset:0x4c00
	s_waitcnt lgkmcnt(7)
	v_mfma_f32_32x32x16_bf16 v[16:31], v[84:87], v[216:219], v[16:31]
	ds_read_b64_tr_b16 v[216:217], v206 offset:0x5400
	ds_read_b64_tr_b16 v[218:219], v206 offset:0x5c00
	s_waitcnt lgkmcnt(7)
	v_mfma_f32_32x32x16_bf16 v[16:31], v[88:91], v[220:223], v[16:31]
	ds_read_b64_tr_b16 v[220:221], v206 offset:0x6400
	ds_read_b64_tr_b16 v[222:223], v206 offset:0x6c00
	s_waitcnt lgkmcnt(7)
	v_mfma_f32_32x32x16_bf16 v[16:31], v[92:95], v[224:227], v[16:31]
	ds_read_b64_tr_b16 v[224:225], v206 offset:0x7400
	ds_read_b64_tr_b16 v[226:227], v206 offset:0x7c00
	ds_write_b128 v213, v[166:169]
	s_waitcnt lgkmcnt(7)
	v_mfma_f32_32x32x16_bf16 v[32:47], v[80:83], v[184:187], v[32:47]
	ds_read_b64_tr_b16 v[184:185], v206 offset:0x4600
	ds_read_b64_tr_b16 v[186:187], v206 offset:0x4e00
	v_exp_f32_e32 v215, v74
	v_exp_f32_e32 v188, v68
	s_waitcnt lgkmcnt(7)
	v_mfma_f32_32x32x16_bf16 v[32:47], v[84:87], v[216:219], v[32:47]
	ds_read_b64_tr_b16 v[216:217], v206 offset:0x5600
	ds_read_b64_tr_b16 v[218:219], v206 offset:0x5e00
	v_exp_f32_e32 v189, v69
	v_exp_f32_e32 v196, v70
	s_waitcnt lgkmcnt(7)
	v_mfma_f32_32x32x16_bf16 v[32:47], v[88:91], v[220:223], v[32:47]
	ds_read_b64_tr_b16 v[220:221], v206 offset:0x6600
	ds_read_b64_tr_b16 v[222:223], v206 offset:0x6e00
	v_exp_f32_e32 v197, v71
	v_exp_f32_e32 v198, v72
	s_waitcnt lgkmcnt(7)
	v_mfma_f32_32x32x16_bf16 v[32:47], v[92:95], v[224:227], v[32:47]
	ds_read_b64_tr_b16 v[224:225], v206 offset:0x7600
	ds_read_b64_tr_b16 v[226:227], v206 offset:0x7e00
	v_exp_f32_e32 v199, v73
	ds_write_b128 v214, v[170:173]
	s_waitcnt lgkmcnt(7)
	v_mfma_f32_32x32x16_bf16 v[48:63], v[80:83], v[184:187], v[48:63]
	s_waitcnt vmcnt(4)
	v_exp_f32_e32 v184, v64
	v_exp_f32_e32 v185, v65
	v_exp_f32_e32 v186, v66
	v_exp_f32_e32 v187, v67
	s_waitcnt lgkmcnt(5)
	v_mfma_f32_32x32x16_bf16 v[48:63], v[84:87], v[216:219], v[48:63]
	v_exp_f32_e32 v219, v78
	v_exp_f32_e32 v216, v75
	s_waitcnt lgkmcnt(3)
	v_mfma_f32_32x32x16_bf16 v[48:63], v[88:91], v[220:223], v[48:63]
	v_exp_f32_e32 v220, v79
	v_exp_f32_e32 v217, v76
	v_exp_f32_e32 v218, v77
	s_waitcnt lgkmcnt(0)
	s_barrier
; #define SBAR() __builtin_amdgcn_sched_barrier(0)
; template <int BOFF> __device__ __forceinline__ void qkt_i(f32x16& p0, f32x16& p1, const int (&kb)[4], const bf16x8* qr) {
;   p0 = f32x16{}; p1 = f32x16{};
; #pragma unroll
;   for (int d0 = 0; d0 < 8; ++d0) { const int off = BOFF + (d0 >> 2) * 128;
;     const bf16x8 b0 = LDSV(kb[d0 & 3] + off), b1 = LDSV(kb[d0 & 3] + off + 8192);
;     p0 = __builtin_amdgcn_mfma_f32_32x32x16_bf16(b0, qr[d0], p0, 0, 0, 0);
;     p1 = __builtin_amdgcn_mfma_f32_32x32x16_bf16(b1, qr[d0], p1, 0, 0, 0); }
; }
; template <int D0, int BOFF> __device__ __forceinline__ void pv_one_i(f32x16& od, int vb, bf16x8 pa0, bf16x8 pa1, bf16x8 pa2, bf16x8 pa3) {
;   const s16x4 l0 = tr_read<BOFF + v_rd_off(D0, 0, 0)>(vb), h0 = tr_read<BOFF + v_rd_off(D0, 0, 1)>(vb), l1 = tr_read<BOFF + v_rd_off(D0, 1, 0)>(vb), h1 = tr_read<BOFF + v_rd_off(D0, 1, 1)>(vb);
;   const s16x4 l2 = tr_read<BOFF + v_rd_off(D0, 2, 0)>(vb), h2 = tr_read<BOFF + v_rd_off(D0, 2, 1)>(vb), l3 = tr_read<BOFF + v_rd_off(D0, 3, 0)>(vb), h3 = tr_read<BOFF + v_rd_off(D0, 3, 1)>(vb);
;   asm volatile("s_waitcnt lgkmcnt(0)" ::: "memory"); SBAR();
;     ...
;   od = __builtin_amdgcn_mfma_f32_32x32x16_bf16(pa0, PK(l0, h0), od, 0, 0, 0);
;   od = __builtin_amdgcn_mfma_f32_32x32x16_bf16(pa1, PK(l1, h1), od, 0, 0, 0);
;   od = __builtin_amdgcn_mfma_f32_32x32x16_bf16(pa2, PK(l2, h2), od, 0, 0, 0);
;   od = __builtin_amdgcn_mfma_f32_32x32x16_bf16(pa3, PK(l3, h3), od, 0, 0, 0);
;     ...
; }
; template <int BOFF> __device__ __forceinline__ void pv_i(f32x16* o, int vb, bf16x8 pa0, bf16x8 pa1, bf16x8 pa2, bf16x8 pa3) {
;   pv_one_i<0, BOFF>(o[0], vb, pa0, pa1, pa2, pa3); pv_one_i<1, BOFF>(o[1], vb, pa0, pa1, pa2, pa3); pv_one_i<2, BOFF>(o[2], vb, pa0, pa1, pa2, pa3); pv_one_i<3, BOFF>(o[3], vb, pa0, pa1, pa2, pa3);
; }
	v_mfma_f32_32x32x16_bf16 v[48:63], v[92:95], v[224:227], v[48:63]
	ds_read_b128 v[64:67], v207
	ds_read_b128 v[68:71], v207 offset:8192
	ds_read_b128 v[162:165], v208
	ds_read_b128 v[166:169], v208 offset:8192
	v_exp_f32_e32 v170, v104
	v_exp_f32_e32 v171, v105
	v_exp_f32_e32 v172, v106
	v_exp_f32_e32 v173, v107
	v_exp_f32_e32 v174, v108
	v_exp_f32_e32 v175, v109
	v_exp_f32_e32 v176, v110
	v_exp_f32_e32 v111, v111
	s_waitcnt lgkmcnt(3)
	v_mfma_f32_32x32x16_bf16 v[80:95], v[64:67], v[142:145], 0
	v_exp_f32_e32 v236, v96
	v_add_f32_e32 v96, 0, v184
	v_add_f32_e32 v96, v185, v96
	v_add_f32_e32 v96, v186, v96
	s_waitcnt lgkmcnt(2)
	v_mfma_f32_32x32x16_bf16 v[64:79], v[68:71], v[142:145], 0
	v_add_f32_e32 v96, v187, v96
	v_add_f32_e32 v96, v188, v96
	v_add_f32_e32 v96, v189, v96
	s_waitcnt lgkmcnt(1)
	v_mfma_f32_32x32x16_bf16 v[80:95], v[162:165], v[138:141], v[80:95]
	v_add_f32_e32 v96, v196, v96
	v_add_f32_e32 v96, v197, v96
	v_add_f32_e32 v96, v198, v96
	s_waitcnt lgkmcnt(0)
	v_mfma_f32_32x32x16_bf16 v[64:79], v[166:169], v[138:141], v[64:79]
	ds_read_b128 v[162:165], v209
	ds_read_b128 v[166:169], v209 offset:8192
	v_add_f32_e32 v96, v199, v96
	v_add_f32_e32 v96, v215, v96
	v_add_f32_e32 v96, v216, v96
	v_add_f32_e32 v96, v217, v96
	v_exp_f32_e32 v237, v97
	s_waitcnt lgkmcnt(1)
	v_mfma_f32_32x32x16_bf16 v[80:95], v[162:165], v[112:115], v[80:95]
	v_add_f32_e32 v96, v218, v96
	v_exp_f32_e32 v238, v98
	v_add_f32_e32 v96, v219, v96
	v_exp_f32_e32 v239, v99
	s_waitcnt lgkmcnt(0)
	v_mfma_f32_32x32x16_bf16 v[64:79], v[166:169], v[112:115], v[64:79]
	ds_read_b128 v[162:165], v210
	ds_read_b128 v[166:169], v210 offset:8192
	v_add_f32_e32 v96, v220, v96
	v_exp_f32_e32 v247, v100
	v_add_f32_e32 v96, v236, v96
	v_exp_f32_e32 v248, v101
	s_waitcnt lgkmcnt(1)
	v_mfma_f32_32x32x16_bf16 v[80:95], v[162:165], v[116:119], v[80:95]
	v_add_f32_e32 v96, v237, v96
	v_exp_f32_e32 v249, v102
	v_add_f32_e32 v96, v238, v96
	v_exp_f32_e32 v252, v103
	s_waitcnt lgkmcnt(0)
	v_mfma_f32_32x32x16_bf16 v[64:79], v[166:169], v[116:119], v[64:79]
	ds_read_b128 v[162:165], v190 offset:0
	ds_read_b128 v[166:169], v190 offset:8192
	v_add_f32_e32 v96, v239, v96
	v_add_f32_e32 v96, v247, v96
	v_add_f32_e32 v96, v248, v96
	v_add_f32_e32 v96, v249, v96
	v_add_f32_e32 v96, v252, v96
	v_add_f32_e32 v96, v170, v96
	s_waitcnt lgkmcnt(1)
	v_mfma_f32_32x32x16_bf16 v[80:95], v[162:165], v[120:123], v[80:95]
	v_add_f32_e32 v96, v171, v96
	v_add_f32_e32 v96, v172, v96
	v_add_f32_e32 v96, v173, v96
	v_add_f32_e32 v96, v174, v96
	v_add_f32_e32 v96, v175, v96
	s_waitcnt lgkmcnt(0)
	v_mfma_f32_32x32x16_bf16 v[64:79], v[166:169], v[120:123], v[64:79]
	ds_read_b128 v[162:165], v191 offset:0
	ds_read_b128 v[166:169], v191 offset:8192
	v_add_f32_e32 v96, v176, v96
	v_add_f32_e32 v181, v111, v96
	v_mov_b32_e32 v183, v181
	s_nop 1
	v_permlane32_swap_b32_e32 v181, v183
	v_pk_add_f32 v[96:97], v[180:181], v[182:183]
	s_waitcnt lgkmcnt(1)
	v_mfma_f32_32x32x16_bf16 v[80:95], v[162:165], v[124:127], v[80:95]
	s_nop 0
	v_add_f32_e32 v96, v128, v96
	v_add_f32_e32 v128, v96, v97
	v_cvt_pk_bf16_f32 v96, v184, v185
	v_cvt_pk_bf16_f32 v97, v186, v187
	s_waitcnt lgkmcnt(0)
	v_mfma_f32_32x32x16_bf16 v[64:79], v[166:169], v[124:127], v[64:79]
	ds_read_b128 v[162:165], v192 offset:0
	ds_read_b128 v[166:169], v192 offset:8192
	v_cvt_pk_bf16_f32 v98, v188, v189
	v_cvt_pk_bf16_f32 v99, v196, v197
	v_cvt_pk_bf16_f32 v100, v198, v199
	v_cvt_pk_bf16_f32 v101, v215, v216
	v_cvt_pk_bf16_f32 v102, v217, v218
	v_cvt_pk_bf16_f32 v103, v219, v220
	s_waitcnt lgkmcnt(1)
	v_mfma_f32_32x32x16_bf16 v[80:95], v[162:165], v[130:133], v[80:95]
	v_cvt_pk_bf16_f32 v104, v236, v237
	v_cvt_pk_bf16_f32 v105, v238, v239
	v_cvt_pk_bf16_f32 v106, v247, v248
	v_cvt_pk_bf16_f32 v107, v249, v252
	v_cvt_pk_bf16_f32 v108, v170, v171
	s_waitcnt lgkmcnt(0)
	v_mfma_f32_32x32x16_bf16 v[64:79], v[166:169], v[130:133], v[64:79]
	ds_read_b128 v[162:165], v193 offset:0
	ds_read_b128 v[166:169], v193 offset:8192
	ds_read_b64_tr_b16 v[180:181], v206 offset:0x8000
	ds_read_b64_tr_b16 v[182:183], v206 offset:0x8800
	ds_read_b64_tr_b16 v[184:185], v206 offset:0x9000
	ds_read_b64_tr_b16 v[186:187], v206 offset:0x9800
	ds_read_b64_tr_b16 v[216:217], v206 offset:0xa000
	ds_read_b64_tr_b16 v[218:219], v206 offset:0xa800
	ds_read_b64_tr_b16 v[220:221], v206 offset:0xb000
	ds_read_b64_tr_b16 v[222:223], v206 offset:0xb800
	v_cvt_pk_bf16_f32 v109, v172, v173
	v_cvt_pk_bf16_f32 v110, v174, v175
	v_cvt_pk_bf16_f32 v111, v176, v111
	s_nop 0
	v_permlane32_swap_b32_e32 v96, v98
	v_permlane32_swap_b32_e32 v97, v99
	s_waitcnt lgkmcnt(9)
	v_mfma_f32_32x32x16_bf16 v[80:95], v[162:165], v[134:137], v[80:95]
	v_permlane32_swap_b32_e32 v100, v102
	v_permlane32_swap_b32_e32 v101, v103
	v_permlane32_swap_b32_e32 v104, v106
	v_permlane32_swap_b32_e32 v105, v107
	v_permlane32_swap_b32_e32 v108, v110
	s_waitcnt lgkmcnt(8)
	v_mfma_f32_32x32x16_bf16 v[64:79], v[166:169], v[134:137], v[64:79]
	v_permlane32_swap_b32_e32 v109, v111
	s_waitcnt vmcnt(0)
	ds_write_b128 v211, v[146:149] offset:16384
	s_nop 0
	s_waitcnt lgkmcnt(7)
	v_mfma_f32_32x32x16_bf16 v[0:15], v[96:99], v[180:183], v[0:15]
	ds_read_b64_tr_b16 v[180:181], v206 offset:0x8200
	ds_read_b64_tr_b16 v[182:183], v206 offset:0x8a00
	v_add_co_u32_e32 v166, vcc, s23, v178
	s_nop 1
	v_addc_co_u32_e32 v167, vcc, -1, v179, vcc
	v_add_co_u32_e32 v170, vcc, s24, v178
	s_nop 1
	v_addc_co_u32_e32 v171, vcc, -1, v179, vcc
	s_waitcnt lgkmcnt(7)
; #define SBAR() __builtin_amdgcn_sched_barrier(0)
; __device__ __forceinline__ void partialSM_fixed(f32x16& p0) {
;   for (int r = 0; r < 16; ++r) p0[r] = __builtin_amdgcn_exp2f(p0[r]);
; }
; template <int D0, int BOFF> __device__ __forceinline__ void pv_one_i(f32x16& od, int vb, bf16x8 pa0, bf16x8 pa1, bf16x8 pa2, bf16x8 pa3) {
;   const s16x4 l0 = tr_read<BOFF + v_rd_off(D0, 0, 0)>(vb), h0 = tr_read<BOFF + v_rd_off(D0, 0, 1)>(vb), l1 = tr_read<BOFF + v_rd_off(D0, 1, 0)>(vb), h1 = tr_read<BOFF + v_rd_off(D0, 1, 1)>(vb);
;   const s16x4 l2 = tr_read<BOFF + v_rd_off(D0, 2, 0)>(vb), h2 = tr_read<BOFF + v_rd_off(D0, 2, 1)>(vb), l3 = tr_read<BOFF + v_rd_off(D0, 3, 0)>(vb), h3 = tr_read<BOFF + v_rd_off(D0, 3, 1)>(vb);
;   asm volatile("s_waitcnt lgkmcnt(0)" ::: "memory"); SBAR();
;     ...
;   od = __builtin_amdgcn_mfma_f32_32x32x16_bf16(pa0, PK(l0, h0), od, 0, 0, 0);
;   od = __builtin_amdgcn_mfma_f32_32x32x16_bf16(pa1, PK(l1, h1), od, 0, 0, 0);
;   od = __builtin_amdgcn_mfma_f32_32x32x16_bf16(pa2, PK(l2, h2), od, 0, 0, 0);
;   od = __builtin_amdgcn_mfma_f32_32x32x16_bf16(pa3, PK(l3, h3), od, 0, 0, 0);
;     ...
; }
; template <int BOFF> __device__ __forceinline__ void pv_i(f32x16* o, int vb, bf16x8 pa0, bf16x8 pa1, bf16x8 pa2, bf16x8 pa3) {
;   pv_one_i<0, BOFF>(o[0], vb, pa0, pa1, pa2, pa3); pv_one_i<1, BOFF>(o[1], vb, pa0, pa1, pa2, pa3); pv_one_i<2, BOFF>(o[2], vb, pa0, pa1, pa2, pa3); pv_one_i<3, BOFF>(o[3], vb, pa0, pa1, pa2, pa3);
; }
	v_mfma_f32_32x32x16_bf16 v[0:15], v[100:103], v[184:187], v[0:15]
	ds_read_b64_tr_b16 v[184:185], v206 offset:0x9200
	ds_read_b64_tr_b16 v[186:187], v206 offset:0x9a00
	global_load_dwordx4 v[162:165], v[166:167], off
	s_nop 0
	global_load_dwordx4 v[166:169], v[166:167], off offset:-512
	s_nop 0
	global_load_dwordx4 v[174:177], v[170:171], off
	s_nop 0
	global_load_dwordx4 v[170:173], v[170:171], off offset:-512
	s_waitcnt lgkmcnt(7)
	v_mfma_f32_32x32x16_bf16 v[0:15], v[104:107], v[216:219], v[0:15]
	ds_read_b64_tr_b16 v[216:217], v206 offset:0xa200
	ds_read_b64_tr_b16 v[218:219], v206 offset:0xaa00
	s_waitcnt lgkmcnt(7)
	v_mfma_f32_32x32x16_bf16 v[0:15], v[108:111], v[220:223], v[0:15]
	ds_read_b64_tr_b16 v[220:221], v206 offset:0xb200
	ds_read_b64_tr_b16 v[222:223], v206 offset:0xba00
	ds_write_b128 v212, v[158:161] offset:16384
	s_waitcnt lgkmcnt(7)
	v_mfma_f32_32x32x16_bf16 v[16:31], v[96:99], v[180:183], v[16:31]
	ds_read_b64_tr_b16 v[180:181], v206 offset:0x8400
	ds_read_b64_tr_b16 v[182:183], v206 offset:0x8c00
	s_waitcnt lgkmcnt(7)
	v_mfma_f32_32x32x16_bf16 v[16:31], v[100:103], v[184:187], v[16:31]
	ds_read_b64_tr_b16 v[184:185], v206 offset:0x9400
	ds_read_b64_tr_b16 v[186:187], v206 offset:0x9c00
	s_waitcnt lgkmcnt(7)
	v_mfma_f32_32x32x16_bf16 v[16:31], v[104:107], v[216:219], v[16:31]
	ds_read_b64_tr_b16 v[216:217], v206 offset:0xa400
	ds_read_b64_tr_b16 v[218:219], v206 offset:0xac00
	s_waitcnt lgkmcnt(7)
	v_mfma_f32_32x32x16_bf16 v[16:31], v[108:111], v[220:223], v[16:31]
	ds_read_b64_tr_b16 v[220:221], v206 offset:0xb400
	ds_read_b64_tr_b16 v[222:223], v206 offset:0xbc00
	ds_write_b128 v213, v[150:153] offset:16384
	s_waitcnt lgkmcnt(7)
	v_mfma_f32_32x32x16_bf16 v[32:47], v[96:99], v[180:183], v[32:47]
	ds_read_b64_tr_b16 v[180:181], v206 offset:0x8600
	ds_read_b64_tr_b16 v[182:183], v206 offset:0x8e00
	v_exp_f32_e32 v215, v92
	v_exp_f32_e32 v188, v86
	s_waitcnt lgkmcnt(7)
	v_mfma_f32_32x32x16_bf16 v[32:47], v[100:103], v[184:187], v[32:47]
	ds_read_b64_tr_b16 v[184:185], v206 offset:0x9600
	ds_read_b64_tr_b16 v[186:187], v206 offset:0x9e00
	v_exp_f32_e32 v189, v87
	v_exp_f32_e32 v196, v88
	s_waitcnt lgkmcnt(7)
	v_mfma_f32_32x32x16_bf16 v[32:47], v[104:107], v[216:219], v[32:47]
	ds_read_b64_tr_b16 v[216:217], v206 offset:0xa600
	ds_read_b64_tr_b16 v[218:219], v206 offset:0xae00
	v_exp_f32_e32 v197, v89
	v_exp_f32_e32 v198, v90
	s_waitcnt lgkmcnt(7)
	v_mfma_f32_32x32x16_bf16 v[32:47], v[108:111], v[220:223], v[32:47]
	ds_read_b64_tr_b16 v[220:221], v206 offset:0xb600
	ds_read_b64_tr_b16 v[222:223], v206 offset:0xbe00
	v_exp_f32_e32 v199, v91
	ds_write_b128 v214, v[154:157] offset:16384
	s_waitcnt lgkmcnt(7)
	v_mfma_f32_32x32x16_bf16 v[48:63], v[96:99], v[180:183], v[48:63]
	s_waitcnt vmcnt(4)
	v_exp_f32_e32 v181, v80
	v_exp_f32_e32 v183, v81
	s_waitcnt lgkmcnt(5)
	v_mfma_f32_32x32x16_bf16 v[48:63], v[100:103], v[184:187], v[48:63]
	v_exp_f32_e32 v184, v82
	v_exp_f32_e32 v185, v83
	v_exp_f32_e32 v186, v84
	v_exp_f32_e32 v187, v85
	s_waitcnt lgkmcnt(3)
	v_mfma_f32_32x32x16_bf16 v[48:63], v[104:107], v[216:219], v[48:63]
	v_exp_f32_e32 v216, v93
	v_exp_f32_e32 v217, v94
	v_exp_f32_e32 v218, v95
	s_waitcnt lgkmcnt(0)
	s_barrier
	v_mfma_f32_32x32x16_bf16 v[48:63], v[108:111], v[220:223], v[48:63]
	ds_read_b128 v[80:83], v207 offset:16384
	ds_read_b128 v[96:99], v207 offset:24576
	ds_read_b128 v[146:149], v208 offset:16384
	ds_read_b128 v[150:153], v208 offset:24576
	v_exp_f32_e32 v154, v72
	v_exp_f32_e32 v155, v73
	v_exp_f32_e32 v156, v74
	v_exp_f32_e32 v157, v75
	v_exp_f32_e32 v158, v76
	v_exp_f32_e32 v159, v77
	v_exp_f32_e32 v160, v78
	v_exp_f32_e32 v79, v79
	s_waitcnt lgkmcnt(3)
	v_mfma_f32_32x32x16_bf16 v[80:95], v[80:83], v[142:145], 0
	v_exp_f32_e32 v236, v64
	v_add_f32_e32 v64, 0, v181
	v_add_f32_e32 v64, v183, v64
	v_add_f32_e32 v64, v184, v64
	s_waitcnt lgkmcnt(2)
	v_mfma_f32_32x32x16_bf16 v[96:111], v[96:99], v[142:145], 0
	v_add_f32_e32 v64, v185, v64
	v_add_f32_e32 v64, v186, v64
	v_add_f32_e32 v64, v187, v64
	s_waitcnt lgkmcnt(1)
	v_mfma_f32_32x32x16_bf16 v[80:95], v[146:149], v[138:141], v[80:95]
	v_add_f32_e32 v64, v188, v64
	v_add_f32_e32 v64, v189, v64
	v_add_f32_e32 v64, v196, v64
	s_waitcnt lgkmcnt(0)
	v_mfma_f32_32x32x16_bf16 v[96:111], v[150:153], v[138:141], v[96:111]
	ds_read_b128 v[146:149], v209 offset:16384
	ds_read_b128 v[150:153], v209 offset:24576
	v_add_f32_e32 v64, v197, v64
	v_add_f32_e32 v64, v198, v64
	v_add_f32_e32 v64, v199, v64
	v_add_f32_e32 v64, v215, v64
	v_exp_f32_e32 v237, v65
	s_waitcnt lgkmcnt(1)
	v_mfma_f32_32x32x16_bf16 v[80:95], v[146:149], v[112:115], v[80:95]
	v_add_f32_e32 v64, v216, v64
	v_exp_f32_e32 v238, v66
	v_add_f32_e32 v64, v217, v64
	v_exp_f32_e32 v239, v67
	s_waitcnt lgkmcnt(0)
	v_mfma_f32_32x32x16_bf16 v[96:111], v[150:153], v[112:115], v[96:111]
	ds_read_b128 v[146:149], v210 offset:16384
	ds_read_b128 v[150:153], v210 offset:24576
	v_add_f32_e32 v64, v218, v64
	v_exp_f32_e32 v247, v68
	v_add_f32_e32 v64, v236, v64
	v_exp_f32_e32 v248, v69
	s_waitcnt lgkmcnt(1)
	v_mfma_f32_32x32x16_bf16 v[80:95], v[146:149], v[116:119], v[80:95]
	v_add_f32_e32 v64, v237, v64
	v_exp_f32_e32 v249, v70
	v_add_f32_e32 v64, v238, v64
	v_exp_f32_e32 v252, v71
	s_waitcnt lgkmcnt(0)
	v_mfma_f32_32x32x16_bf16 v[96:111], v[150:153], v[116:119], v[96:111]
	ds_read_b128 v[146:149], v190 offset:16384
	ds_read_b128 v[150:153], v190 offset:24576
	v_add_f32_e32 v64, v239, v64
	v_add_f32_e32 v64, v247, v64
	v_add_f32_e32 v64, v248, v64
	v_add_f32_e32 v64, v249, v64
	v_add_f32_e32 v64, v252, v64
	v_add_f32_e32 v64, v154, v64
	s_waitcnt lgkmcnt(1)
; #define SBAR() __builtin_amdgcn_sched_barrier(0)
; __device__ __forceinline__ void partialSM_fixed(f32x16& p0) {
;   for (int r = 0; r < 16; ++r) p0[r] = __builtin_amdgcn_exp2f(p0[r]);
; }
; template <int D0, int BOFF> __device__ __forceinline__ void pv_one_i(f32x16& od, int vb, bf16x8 pa0, bf16x8 pa1, bf16x8 pa2, bf16x8 pa3) {
;   const s16x4 l0 = tr_read<BOFF + v_rd_off(D0, 0, 0)>(vb), h0 = tr_read<BOFF + v_rd_off(D0, 0, 1)>(vb), l1 = tr_read<BOFF + v_rd_off(D0, 1, 0)>(vb), h1 = tr_read<BOFF + v_rd_off(D0, 1, 1)>(vb);
;   const s16x4 l2 = tr_read<BOFF + v_rd_off(D0, 2, 0)>(vb), h2 = tr_read<BOFF + v_rd_off(D0, 2, 1)>(vb), l3 = tr_read<BOFF + v_rd_off(D0, 3, 0)>(vb), h3 = tr_read<BOFF + v_rd_off(D0, 3, 1)>(vb);
;   asm volatile("s_waitcnt lgkmcnt(0)" ::: "memory"); SBAR();
;     ...
;   od = __builtin_amdgcn_mfma_f32_32x32x16_bf16(pa0, PK(l0, h0), od, 0, 0, 0);
;   od = __builtin_amdgcn_mfma_f32_32x32x16_bf16(pa1, PK(l1, h1), od, 0, 0, 0);
;   od = __builtin_amdgcn_mfma_f32_32x32x16_bf16(pa2, PK(l2, h2), od, 0, 0, 0);
;   od = __builtin_amdgcn_mfma_f32_32x32x16_bf16(pa3, PK(l3, h3), od, 0, 0, 0);
;     ...
; }
; template <int BOFF> __device__ __forceinline__ void pv_i(f32x16* o, int vb, bf16x8 pa0, bf16x8 pa1, bf16x8 pa2, bf16x8 pa3) {
;   pv_one_i<0, BOFF>(o[0], vb, pa0, pa1, pa2, pa3); pv_one_i<1, BOFF>(o[1], vb, pa0, pa1, pa2, pa3); pv_one_i<2, BOFF>(o[2], vb, pa0, pa1, pa2, pa3); pv_one_i<3, BOFF>(o[3], vb, pa0, pa1, pa2, pa3);
; }
	v_mfma_f32_32x32x16_bf16 v[80:95], v[146:149], v[120:123], v[80:95]
	v_add_f32_e32 v64, v155, v64
	v_add_f32_e32 v64, v156, v64
	v_add_f32_e32 v64, v157, v64
	v_add_f32_e32 v64, v158, v64
	v_add_f32_e32 v64, v159, v64
	s_waitcnt lgkmcnt(0)
	v_mfma_f32_32x32x16_bf16 v[96:111], v[150:153], v[120:123], v[96:111]
	ds_read_b128 v[146:149], v191 offset:16384
	ds_read_b128 v[150:153], v191 offset:24576
	v_add_f32_e32 v64, v160, v64
	v_add_f32_e32 v180, v79, v64
	v_cvt_pk_bf16_f32 v64, v181, v183
	v_cvt_pk_bf16_f32 v65, v184, v185
	v_cvt_pk_bf16_f32 v66, v186, v187
	v_cvt_pk_bf16_f32 v67, v188, v189
	s_waitcnt lgkmcnt(1)
	v_mfma_f32_32x32x16_bf16 v[80:95], v[146:149], v[124:127], v[80:95]
	v_cvt_pk_bf16_f32 v68, v196, v197
	v_cvt_pk_bf16_f32 v69, v198, v199
	v_cvt_pk_bf16_f32 v70, v215, v216
	v_cvt_pk_bf16_f32 v71, v217, v218
	v_cvt_pk_bf16_f32 v72, v236, v237
	s_waitcnt lgkmcnt(0)
	v_mfma_f32_32x32x16_bf16 v[96:111], v[150:153], v[124:127], v[96:111]
	ds_read_b128 v[146:149], v192 offset:16384
	ds_read_b128 v[150:153], v192 offset:24576
	v_cvt_pk_bf16_f32 v73, v238, v239
	v_cvt_pk_bf16_f32 v74, v247, v248
	v_cvt_pk_bf16_f32 v75, v249, v252
	v_cvt_pk_bf16_f32 v76, v154, v155
	v_cvt_pk_bf16_f32 v77, v156, v157
	v_cvt_pk_bf16_f32 v78, v158, v159
	s_waitcnt lgkmcnt(1)
	v_mfma_f32_32x32x16_bf16 v[80:95], v[146:149], v[130:133], v[80:95]
	v_cvt_pk_bf16_f32 v79, v160, v79
	v_mov_b32_e32 v182, v180
	v_permlane32_swap_b32_e32 v64, v66
	v_permlane32_swap_b32_e32 v65, v67
	v_permlane32_swap_b32_e32 v68, v70
	s_waitcnt lgkmcnt(0)
	v_mfma_f32_32x32x16_bf16 v[96:111], v[150:153], v[130:133], v[96:111]
	ds_read_b128 v[146:149], v193 offset:16384
	ds_read_b128 v[150:153], v193 offset:24576
	ds_read_b64_tr_b16 v[184:185], v206 offset:0
	ds_read_b64_tr_b16 v[186:187], v206 offset:0x800
	ds_read_b64_tr_b16 v[216:217], v206 offset:0x1000
	ds_read_b64_tr_b16 v[218:219], v206 offset:0x1800
	ds_read_b64_tr_b16 v[220:221], v206 offset:0x2000
	ds_read_b64_tr_b16 v[222:223], v206 offset:0x2800
	ds_read_b64_tr_b16 v[224:225], v206 offset:0x3000
	ds_read_b64_tr_b16 v[226:227], v206 offset:0x3800
	v_permlane32_swap_b32_e32 v69, v71
	v_permlane32_swap_b32_e32 v72, v74
	v_permlane32_swap_b32_e32 v73, v75
	v_permlane32_swap_b32_e32 v76, v78
	v_permlane32_swap_b32_e32 v77, v79
	v_permlane32_swap_b32_e32 v180, v182
	s_waitcnt lgkmcnt(9)
	v_mfma_f32_32x32x16_bf16 v[80:95], v[146:149], v[134:137], v[80:95]
	s_waitcnt lgkmcnt(8)
	v_mfma_f32_32x32x16_bf16 v[96:111], v[150:153], v[134:137], v[96:111]
	s_waitcnt vmcnt(0)
	ds_write_b128 v211, v[162:165] offset:32768
	s_nop 0
	s_waitcnt lgkmcnt(7)
	v_mfma_f32_32x32x16_bf16 v[0:15], v[64:67], v[184:187], v[0:15]
	ds_read_b64_tr_b16 v[184:185], v206 offset:0x200
	ds_read_b64_tr_b16 v[186:187], v206 offset:0xa00
	v_add_co_u32_e32 v150, vcc, s25, v178
	s_nop 1
	v_addc_co_u32_e32 v151, vcc, -1, v179, vcc
	v_add_co_u32_e32 v154, vcc, s45, v178
	s_nop 1
	v_addc_co_u32_e32 v155, vcc, -1, v179, vcc
	s_waitcnt lgkmcnt(7)
	v_mfma_f32_32x32x16_bf16 v[0:15], v[68:71], v[216:219], v[0:15]
	ds_read_b64_tr_b16 v[216:217], v206 offset:0x1200
	ds_read_b64_tr_b16 v[218:219], v206 offset:0x1a00
	global_load_dwordx4 v[146:149], v[150:151], off
	s_nop 0
	global_load_dwordx4 v[150:153], v[150:151], off offset:-512
	s_nop 0
	global_load_dwordx4 v[158:161], v[154:155], off
	s_nop 0
	global_load_dwordx4 v[154:157], v[154:155], off offset:-512
	s_waitcnt lgkmcnt(7)
	v_mfma_f32_32x32x16_bf16 v[0:15], v[72:75], v[220:223], v[0:15]
	ds_read_b64_tr_b16 v[220:221], v206 offset:0x2200
	ds_read_b64_tr_b16 v[222:223], v206 offset:0x2a00
	s_waitcnt lgkmcnt(7)
	v_mfma_f32_32x32x16_bf16 v[0:15], v[76:79], v[224:227], v[0:15]
	ds_read_b64_tr_b16 v[224:225], v206 offset:0x3200
	ds_read_b64_tr_b16 v[226:227], v206 offset:0x3a00
	ds_write_b128 v212, v[174:177] offset:32768
	s_waitcnt lgkmcnt(7)
	v_mfma_f32_32x32x16_bf16 v[16:31], v[64:67], v[184:187], v[16:31]
	ds_read_b64_tr_b16 v[184:185], v206 offset:0x400
	ds_read_b64_tr_b16 v[186:187], v206 offset:0xc00
	s_waitcnt lgkmcnt(7)
	v_mfma_f32_32x32x16_bf16 v[16:31], v[68:71], v[216:219], v[16:31]
	ds_read_b64_tr_b16 v[216:217], v206 offset:0x1400
	ds_read_b64_tr_b16 v[218:219], v206 offset:0x1c00
	s_waitcnt lgkmcnt(7)
	v_mfma_f32_32x32x16_bf16 v[16:31], v[72:75], v[220:223], v[16:31]
	ds_read_b64_tr_b16 v[220:221], v206 offset:0x2400
	ds_read_b64_tr_b16 v[222:223], v206 offset:0x2c00
	s_waitcnt lgkmcnt(7)
	v_mfma_f32_32x32x16_bf16 v[16:31], v[76:79], v[224:227], v[16:31]
	ds_read_b64_tr_b16 v[224:225], v206 offset:0x3400
	ds_read_b64_tr_b16 v[226:227], v206 offset:0x3c00
	ds_write_b128 v213, v[166:169] offset:32768
	s_waitcnt lgkmcnt(7)
	v_mfma_f32_32x32x16_bf16 v[32:47], v[64:67], v[184:187], v[32:47]
	ds_read_b64_tr_b16 v[184:185], v206 offset:0x600
	ds_read_b64_tr_b16 v[186:187], v206 offset:0xe00
	v_exp_f32_e32 v215, v90
	v_exp_f32_e32 v188, v84
	s_waitcnt lgkmcnt(7)
	v_mfma_f32_32x32x16_bf16 v[32:47], v[68:71], v[216:219], v[32:47]
	ds_read_b64_tr_b16 v[216:217], v206 offset:0x1600
	ds_read_b64_tr_b16 v[218:219], v206 offset:0x1e00
	v_exp_f32_e32 v189, v85
	v_exp_f32_e32 v196, v86
	s_waitcnt lgkmcnt(7)
	v_mfma_f32_32x32x16_bf16 v[32:47], v[72:75], v[220:223], v[32:47]
	ds_read_b64_tr_b16 v[220:221], v206 offset:0x2600
	ds_read_b64_tr_b16 v[222:223], v206 offset:0x2e00
	v_exp_f32_e32 v197, v87
	v_exp_f32_e32 v198, v88
	s_waitcnt lgkmcnt(7)
	v_mfma_f32_32x32x16_bf16 v[32:47], v[76:79], v[224:227], v[32:47]
	ds_read_b64_tr_b16 v[224:225], v206 offset:0x3600
	ds_read_b64_tr_b16 v[226:227], v206 offset:0x3e00
	v_exp_f32_e32 v199, v89
	ds_write_b128 v214, v[170:173] offset:32768
	s_waitcnt lgkmcnt(7)
	v_mfma_f32_32x32x16_bf16 v[48:63], v[64:67], v[184:187], v[48:63]
	s_waitcnt vmcnt(4)
	v_exp_f32_e32 v184, v80
	v_exp_f32_e32 v185, v81
	v_exp_f32_e32 v186, v82
	v_exp_f32_e32 v187, v83
	s_waitcnt lgkmcnt(5)
	v_mfma_f32_32x32x16_bf16 v[48:63], v[68:71], v[216:219], v[48:63]
	v_exp_f32_e32 v219, v94
	v_exp_f32_e32 v216, v91
	s_waitcnt lgkmcnt(3)
	v_mfma_f32_32x32x16_bf16 v[48:63], v[72:75], v[220:223], v[48:63]
	v_exp_f32_e32 v220, v95
	v_exp_f32_e32 v217, v92
	v_exp_f32_e32 v218, v93
	s_waitcnt lgkmcnt(0)
	s_barrier
; #define SBAR() __builtin_amdgcn_sched_barrier(0)
; template <int BOFF> __device__ __forceinline__ void qkt_i(f32x16& p0, f32x16& p1, const int (&kb)[4], const bf16x8* qr) {
;   p0 = f32x16{}; p1 = f32x16{};
; #pragma unroll
;   for (int d0 = 0; d0 < 8; ++d0) { const int off = BOFF + (d0 >> 2) * 128;
;     const bf16x8 b0 = LDSV(kb[d0 & 3] + off), b1 = LDSV(kb[d0 & 3] + off + 8192);
;     p0 = __builtin_amdgcn_mfma_f32_32x32x16_bf16(b0, qr[d0], p0, 0, 0, 0);
;     p1 = __builtin_amdgcn_mfma_f32_32x32x16_bf16(b1, qr[d0], p1, 0, 0, 0); }
; }
; template <int D0, int BOFF> __device__ __forceinline__ void pv_one_i(f32x16& od, int vb, bf16x8 pa0, bf16x8 pa1, bf16x8 pa2, bf16x8 pa3) {
;   const s16x4 l0 = tr_read<BOFF + v_rd_off(D0, 0, 0)>(vb), h0 = tr_read<BOFF + v_rd_off(D0, 0, 1)>(vb), l1 = tr_read<BOFF + v_rd_off(D0, 1, 0)>(vb), h1 = tr_read<BOFF + v_rd_off(D0, 1, 1)>(vb);
;   const s16x4 l2 = tr_read<BOFF + v_rd_off(D0, 2, 0)>(vb), h2 = tr_read<BOFF + v_rd_off(D0, 2, 1)>(vb), l3 = tr_read<BOFF + v_rd_off(D0, 3, 0)>(vb), h3 = tr_read<BOFF + v_rd_off(D0, 3, 1)>(vb);
;   asm volatile("s_waitcnt lgkmcnt(0)" ::: "memory"); SBAR();
;     ...
;   od = __builtin_amdgcn_mfma_f32_32x32x16_bf16(pa0, PK(l0, h0), od, 0, 0, 0);
;   od = __builtin_amdgcn_mfma_f32_32x32x16_bf16(pa1, PK(l1, h1), od, 0, 0, 0);
;   od = __builtin_amdgcn_mfma_f32_32x32x16_bf16(pa2, PK(l2, h2), od, 0, 0, 0);
;   od = __builtin_amdgcn_mfma_f32_32x32x16_bf16(pa3, PK(l3, h3), od, 0, 0, 0);
;     ...
; }
; template <int BOFF> __device__ __forceinline__ void pv_i(f32x16* o, int vb, bf16x8 pa0, bf16x8 pa1, bf16x8 pa2, bf16x8 pa3) {
;   pv_one_i<0, BOFF>(o[0], vb, pa0, pa1, pa2, pa3); pv_one_i<1, BOFF>(o[1], vb, pa0, pa1, pa2, pa3); pv_one_i<2, BOFF>(o[2], vb, pa0, pa1, pa2, pa3); pv_one_i<3, BOFF>(o[3], vb, pa0, pa1, pa2, pa3);
; }
	v_mfma_f32_32x32x16_bf16 v[48:63], v[76:79], v[224:227], v[48:63]
	ds_read_b128 v[64:67], v207 offset:32768
	ds_read_b128 v[80:83], v207 offset:40960
	ds_read_b128 v[162:165], v208 offset:32768
	ds_read_b128 v[166:169], v208 offset:40960
	v_exp_f32_e32 v170, v104
	v_exp_f32_e32 v171, v105
	v_exp_f32_e32 v172, v106
	v_exp_f32_e32 v173, v107
	v_exp_f32_e32 v174, v108
	v_exp_f32_e32 v175, v109
	v_exp_f32_e32 v176, v110
	v_exp_f32_e32 v111, v111
	s_waitcnt lgkmcnt(3)
	v_mfma_f32_32x32x16_bf16 v[64:79], v[64:67], v[142:145], 0
	v_exp_f32_e32 v236, v96
	v_add_f32_e32 v96, 0, v184
	v_add_f32_e32 v96, v185, v96
	v_add_f32_e32 v96, v186, v96
	s_waitcnt lgkmcnt(2)
	v_mfma_f32_32x32x16_bf16 v[80:95], v[80:83], v[142:145], 0
	v_add_f32_e32 v96, v187, v96
	v_add_f32_e32 v96, v188, v96
	v_add_f32_e32 v96, v189, v96
	s_waitcnt lgkmcnt(1)
	v_mfma_f32_32x32x16_bf16 v[64:79], v[162:165], v[138:141], v[64:79]
	v_add_f32_e32 v96, v196, v96
	v_add_f32_e32 v96, v197, v96
	v_add_f32_e32 v96, v198, v96
	s_waitcnt lgkmcnt(0)
	v_mfma_f32_32x32x16_bf16 v[80:95], v[166:169], v[138:141], v[80:95]
	ds_read_b128 v[162:165], v209 offset:32768
	ds_read_b128 v[166:169], v209 offset:40960
	v_add_f32_e32 v96, v199, v96
	v_add_f32_e32 v96, v215, v96
	v_add_f32_e32 v96, v216, v96
	v_add_f32_e32 v96, v217, v96
	v_exp_f32_e32 v237, v97
	s_waitcnt lgkmcnt(1)
	v_mfma_f32_32x32x16_bf16 v[64:79], v[162:165], v[112:115], v[64:79]
	v_add_f32_e32 v96, v218, v96
	v_exp_f32_e32 v238, v98
	v_add_f32_e32 v96, v219, v96
	v_exp_f32_e32 v239, v99
	s_waitcnt lgkmcnt(0)
	v_mfma_f32_32x32x16_bf16 v[80:95], v[166:169], v[112:115], v[80:95]
	ds_read_b128 v[162:165], v210 offset:32768
	ds_read_b128 v[166:169], v210 offset:40960
	v_add_f32_e32 v96, v220, v96
	v_exp_f32_e32 v247, v100
	v_add_f32_e32 v96, v236, v96
	v_exp_f32_e32 v248, v101
	s_waitcnt lgkmcnt(1)
	v_mfma_f32_32x32x16_bf16 v[64:79], v[162:165], v[116:119], v[64:79]
	v_add_f32_e32 v96, v237, v96
	v_exp_f32_e32 v249, v102
	v_add_f32_e32 v96, v238, v96
	v_exp_f32_e32 v252, v103
	s_waitcnt lgkmcnt(0)
	v_mfma_f32_32x32x16_bf16 v[80:95], v[166:169], v[116:119], v[80:95]
	ds_read_b128 v[162:165], v190 offset:32768
	ds_read_b128 v[166:169], v190 offset:40960
	v_add_f32_e32 v96, v239, v96
	v_add_f32_e32 v96, v247, v96
	v_add_f32_e32 v96, v248, v96
	v_add_f32_e32 v96, v249, v96
	v_add_f32_e32 v96, v252, v96
	v_add_f32_e32 v96, v170, v96
	s_waitcnt lgkmcnt(1)
	v_mfma_f32_32x32x16_bf16 v[64:79], v[162:165], v[120:123], v[64:79]
	v_add_f32_e32 v96, v171, v96
	v_add_f32_e32 v96, v172, v96
	v_add_f32_e32 v96, v173, v96
	v_add_f32_e32 v96, v174, v96
	v_add_f32_e32 v96, v175, v96
	s_waitcnt lgkmcnt(0)
	v_mfma_f32_32x32x16_bf16 v[80:95], v[166:169], v[120:123], v[80:95]
	ds_read_b128 v[162:165], v191 offset:32768
	ds_read_b128 v[166:169], v191 offset:40960
	v_add_f32_e32 v96, v176, v96
	v_add_f32_e32 v181, v111, v96
	v_mov_b32_e32 v183, v181
	s_nop 1
	v_permlane32_swap_b32_e32 v181, v183
	v_pk_add_f32 v[96:97], v[180:181], v[182:183]
	s_waitcnt lgkmcnt(1)
	v_mfma_f32_32x32x16_bf16 v[64:79], v[162:165], v[124:127], v[64:79]
	s_nop 0
	v_add_f32_e32 v96, v128, v96
	v_add_f32_e32 v128, v96, v97
	v_cvt_pk_bf16_f32 v96, v184, v185
	v_cvt_pk_bf16_f32 v97, v186, v187
	s_waitcnt lgkmcnt(0)
	v_mfma_f32_32x32x16_bf16 v[80:95], v[166:169], v[124:127], v[80:95]
	ds_read_b128 v[162:165], v192 offset:32768
	ds_read_b128 v[166:169], v192 offset:40960
	v_cvt_pk_bf16_f32 v98, v188, v189
	v_cvt_pk_bf16_f32 v99, v196, v197
	v_cvt_pk_bf16_f32 v100, v198, v199
	v_cvt_pk_bf16_f32 v101, v215, v216
	v_cvt_pk_bf16_f32 v102, v217, v218
	v_cvt_pk_bf16_f32 v103, v219, v220
	s_waitcnt lgkmcnt(1)
	v_mfma_f32_32x32x16_bf16 v[64:79], v[162:165], v[130:133], v[64:79]
	v_cvt_pk_bf16_f32 v104, v236, v237
	v_cvt_pk_bf16_f32 v105, v238, v239
	v_cvt_pk_bf16_f32 v106, v247, v248
	v_cvt_pk_bf16_f32 v107, v249, v252
	v_cvt_pk_bf16_f32 v108, v170, v171
	s_waitcnt lgkmcnt(0)
	v_mfma_f32_32x32x16_bf16 v[80:95], v[166:169], v[130:133], v[80:95]
	ds_read_b128 v[162:165], v193 offset:32768
	ds_read_b128 v[166:169], v193 offset:40960
	ds_read_b64_tr_b16 v[180:181], v206 offset:0x4000
	ds_read_b64_tr_b16 v[182:183], v206 offset:0x4800
	ds_read_b64_tr_b16 v[184:185], v206 offset:0x5000
	ds_read_b64_tr_b16 v[186:187], v206 offset:0x5800
	ds_read_b64_tr_b16 v[216:217], v206 offset:0x6000
	ds_read_b64_tr_b16 v[218:219], v206 offset:0x6800
	ds_read_b64_tr_b16 v[220:221], v206 offset:0x7000
	ds_read_b64_tr_b16 v[222:223], v206 offset:0x7800
	v_cvt_pk_bf16_f32 v109, v172, v173
	v_cvt_pk_bf16_f32 v110, v174, v175
	v_cvt_pk_bf16_f32 v111, v176, v111
	s_nop 0
	v_permlane32_swap_b32_e32 v96, v98
	v_permlane32_swap_b32_e32 v97, v99
	s_waitcnt lgkmcnt(9)
	v_mfma_f32_32x32x16_bf16 v[64:79], v[162:165], v[134:137], v[64:79]
	v_permlane32_swap_b32_e32 v100, v102
	v_permlane32_swap_b32_e32 v101, v103
	v_permlane32_swap_b32_e32 v104, v106
	v_permlane32_swap_b32_e32 v105, v107
	v_permlane32_swap_b32_e32 v108, v110
	s_waitcnt lgkmcnt(8)
	v_mfma_f32_32x32x16_bf16 v[80:95], v[166:169], v[134:137], v[80:95]
	v_permlane32_swap_b32_e32 v109, v111
	s_waitcnt vmcnt(0)
	ds_write_b128 v211, v[146:149]
	s_nop 0
	s_waitcnt lgkmcnt(7)
	v_mfma_f32_32x32x16_bf16 v[0:15], v[96:99], v[180:183], v[0:15]
	ds_read_b64_tr_b16 v[180:181], v206 offset:0x4200
	ds_read_b64_tr_b16 v[182:183], v206 offset:0x4a00
	v_add_co_u32_e32 v166, vcc, s52, v178
	s_nop 1
	v_addc_co_u32_e32 v167, vcc, -1, v179, vcc
	v_add_co_u32_e32 v170, vcc, s53, v178
	s_nop 1
	v_addc_co_u32_e32 v171, vcc, -1, v179, vcc
	s_waitcnt lgkmcnt(7)
; #define SBAR() __builtin_amdgcn_sched_barrier(0)
; __device__ __forceinline__ void partialSM_fixed(f32x16& p0) {
;   for (int r = 0; r < 16; ++r) p0[r] = __builtin_amdgcn_exp2f(p0[r]);
; }
; template <int D0, int BOFF> __device__ __forceinline__ void pv_one_i(f32x16& od, int vb, bf16x8 pa0, bf16x8 pa1, bf16x8 pa2, bf16x8 pa3) {
;   const s16x4 l0 = tr_read<BOFF + v_rd_off(D0, 0, 0)>(vb), h0 = tr_read<BOFF + v_rd_off(D0, 0, 1)>(vb), l1 = tr_read<BOFF + v_rd_off(D0, 1, 0)>(vb), h1 = tr_read<BOFF + v_rd_off(D0, 1, 1)>(vb);
;   const s16x4 l2 = tr_read<BOFF + v_rd_off(D0, 2, 0)>(vb), h2 = tr_read<BOFF + v_rd_off(D0, 2, 1)>(vb), l3 = tr_read<BOFF + v_rd_off(D0, 3, 0)>(vb), h3 = tr_read<BOFF + v_rd_off(D0, 3, 1)>(vb);
;   asm volatile("s_waitcnt lgkmcnt(0)" ::: "memory"); SBAR();
;     ...
;   od = __builtin_amdgcn_mfma_f32_32x32x16_bf16(pa0, PK(l0, h0), od, 0, 0, 0);
;   od = __builtin_amdgcn_mfma_f32_32x32x16_bf16(pa1, PK(l1, h1), od, 0, 0, 0);
;   od = __builtin_amdgcn_mfma_f32_32x32x16_bf16(pa2, PK(l2, h2), od, 0, 0, 0);
;   od = __builtin_amdgcn_mfma_f32_32x32x16_bf16(pa3, PK(l3, h3), od, 0, 0, 0);
;     ...
; }
; template <int BOFF> __device__ __forceinline__ void pv_i(f32x16* o, int vb, bf16x8 pa0, bf16x8 pa1, bf16x8 pa2, bf16x8 pa3) {
;   pv_one_i<0, BOFF>(o[0], vb, pa0, pa1, pa2, pa3); pv_one_i<1, BOFF>(o[1], vb, pa0, pa1, pa2, pa3); pv_one_i<2, BOFF>(o[2], vb, pa0, pa1, pa2, pa3); pv_one_i<3, BOFF>(o[3], vb, pa0, pa1, pa2, pa3);
; }
	v_mfma_f32_32x32x16_bf16 v[0:15], v[100:103], v[184:187], v[0:15]
	ds_read_b64_tr_b16 v[184:185], v206 offset:0x5200
	ds_read_b64_tr_b16 v[186:187], v206 offset:0x5a00
	global_load_dwordx4 v[162:165], v[166:167], off
	s_nop 0
	global_load_dwordx4 v[166:169], v[166:167], off offset:-512
	s_nop 0
	global_load_dwordx4 v[174:177], v[170:171], off
	s_nop 0
	global_load_dwordx4 v[170:173], v[170:171], off offset:-512
	s_waitcnt lgkmcnt(7)
	v_mfma_f32_32x32x16_bf16 v[0:15], v[104:107], v[216:219], v[0:15]
	ds_read_b64_tr_b16 v[216:217], v206 offset:0x6200
	ds_read_b64_tr_b16 v[218:219], v206 offset:0x6a00
	s_waitcnt lgkmcnt(7)
	v_mfma_f32_32x32x16_bf16 v[0:15], v[108:111], v[220:223], v[0:15]
	ds_read_b64_tr_b16 v[220:221], v206 offset:0x7200
	ds_read_b64_tr_b16 v[222:223], v206 offset:0x7a00
	ds_write_b128 v212, v[158:161]
	s_waitcnt lgkmcnt(7)
	v_mfma_f32_32x32x16_bf16 v[16:31], v[96:99], v[180:183], v[16:31]
	ds_read_b64_tr_b16 v[180:181], v206 offset:0x4400
	ds_read_b64_tr_b16 v[182:183], v206 offset:0x4c00
	s_waitcnt lgkmcnt(7)
	v_mfma_f32_32x32x16_bf16 v[16:31], v[100:103], v[184:187], v[16:31]
	ds_read_b64_tr_b16 v[184:185], v206 offset:0x5400
	ds_read_b64_tr_b16 v[186:187], v206 offset:0x5c00
	s_waitcnt lgkmcnt(7)
	v_mfma_f32_32x32x16_bf16 v[16:31], v[104:107], v[216:219], v[16:31]
	ds_read_b64_tr_b16 v[216:217], v206 offset:0x6400
	ds_read_b64_tr_b16 v[218:219], v206 offset:0x6c00
	s_waitcnt lgkmcnt(7)
	v_mfma_f32_32x32x16_bf16 v[16:31], v[108:111], v[220:223], v[16:31]
	ds_read_b64_tr_b16 v[220:221], v206 offset:0x7400
	ds_read_b64_tr_b16 v[222:223], v206 offset:0x7c00
	ds_write_b128 v213, v[150:153]
	s_waitcnt lgkmcnt(7)
	v_mfma_f32_32x32x16_bf16 v[32:47], v[96:99], v[180:183], v[32:47]
	ds_read_b64_tr_b16 v[180:181], v206 offset:0x4600
	ds_read_b64_tr_b16 v[182:183], v206 offset:0x4e00
	v_exp_f32_e32 v188, v72
	v_exp_f32_e32 v189, v73
	s_waitcnt lgkmcnt(7)
	v_mfma_f32_32x32x16_bf16 v[32:47], v[100:103], v[184:187], v[32:47]
	ds_read_b64_tr_b16 v[184:185], v206 offset:0x5600
	ds_read_b64_tr_b16 v[186:187], v206 offset:0x5e00
	v_exp_f32_e32 v196, v74
	v_exp_f32_e32 v197, v75
	s_waitcnt lgkmcnt(7)
	v_mfma_f32_32x32x16_bf16 v[32:47], v[104:107], v[216:219], v[32:47]
	ds_read_b64_tr_b16 v[216:217], v206 offset:0x6600
	ds_read_b64_tr_b16 v[218:219], v206 offset:0x6e00
	v_exp_f32_e32 v198, v76
	v_exp_f32_e32 v199, v77
	s_waitcnt lgkmcnt(7)
	v_mfma_f32_32x32x16_bf16 v[32:47], v[108:111], v[220:223], v[32:47]
	ds_read_b64_tr_b16 v[220:221], v206 offset:0x7600
	ds_read_b64_tr_b16 v[222:223], v206 offset:0x7e00
	ds_write_b128 v214, v[154:157]
	s_waitcnt lgkmcnt(7)
	v_mfma_f32_32x32x16_bf16 v[48:63], v[96:99], v[180:183], v[48:63]
	s_waitcnt vmcnt(4)
	v_exp_f32_e32 v180, v64
	v_exp_f32_e32 v181, v65
	v_exp_f32_e32 v182, v66
	v_exp_f32_e32 v183, v67
	s_waitcnt lgkmcnt(5)
	v_mfma_f32_32x32x16_bf16 v[48:63], v[100:103], v[184:187], v[48:63]
	v_exp_f32_e32 v184, v68
	v_exp_f32_e32 v185, v69
	v_exp_f32_e32 v186, v70
	v_exp_f32_e32 v187, v71
	s_waitcnt lgkmcnt(3)
	v_mfma_f32_32x32x16_bf16 v[48:63], v[104:107], v[216:219], v[48:63]
	v_exp_f32_e32 v216, v78
	v_exp_f32_e32 v217, v79
	s_waitcnt lgkmcnt(0)
	s_barrier
	v_mfma_f32_32x32x16_bf16 v[48:63], v[108:111], v[220:223], v[48:63]
	ds_read_b128 v[64:67], v207
	ds_read_b128 v[68:71], v207 offset:8192
	ds_read_b128 v[146:149], v208
	ds_read_b128 v[150:153], v208 offset:8192
	v_exp_f32_e32 v154, v88
	v_exp_f32_e32 v155, v89
	v_exp_f32_e32 v156, v90
	v_exp_f32_e32 v157, v91
	v_exp_f32_e32 v158, v92
	v_exp_f32_e32 v159, v93
	v_exp_f32_e32 v160, v94
	v_exp_f32_e32 v95, v95
	s_waitcnt lgkmcnt(3)
	v_mfma_f32_32x32x16_bf16 v[96:111], v[64:67], v[142:145], 0
	v_exp_f32_e32 v236, v80
	v_add_f32_e32 v80, 0, v180
	v_add_f32_e32 v80, v181, v80
	v_add_f32_e32 v80, v182, v80
	s_waitcnt lgkmcnt(2)
	v_mfma_f32_32x32x16_bf16 v[64:79], v[68:71], v[142:145], 0
	v_add_f32_e32 v80, v183, v80
	v_add_f32_e32 v80, v184, v80
	v_add_f32_e32 v80, v185, v80
	s_waitcnt lgkmcnt(1)
	v_mfma_f32_32x32x16_bf16 v[96:111], v[146:149], v[138:141], v[96:111]
	v_add_f32_e32 v80, v186, v80
	v_add_f32_e32 v80, v187, v80
	v_add_f32_e32 v80, v188, v80
	s_waitcnt lgkmcnt(0)
	v_mfma_f32_32x32x16_bf16 v[64:79], v[150:153], v[138:141], v[64:79]
	ds_read_b128 v[146:149], v209
	ds_read_b128 v[150:153], v209 offset:8192
	v_add_f32_e32 v80, v189, v80
	v_add_f32_e32 v80, v196, v80
	v_add_f32_e32 v80, v197, v80
	v_add_f32_e32 v80, v198, v80
	v_exp_f32_e32 v237, v81
	s_waitcnt lgkmcnt(1)
	v_mfma_f32_32x32x16_bf16 v[96:111], v[146:149], v[112:115], v[96:111]
	v_add_f32_e32 v80, v199, v80
	v_exp_f32_e32 v238, v82
	v_add_f32_e32 v80, v216, v80
	v_exp_f32_e32 v239, v83
	s_waitcnt lgkmcnt(0)
	v_mfma_f32_32x32x16_bf16 v[64:79], v[150:153], v[112:115], v[64:79]
	ds_read_b128 v[146:149], v210
	ds_read_b128 v[150:153], v210 offset:8192
	v_add_f32_e32 v80, v217, v80
	v_exp_f32_e32 v247, v84
	v_add_f32_e32 v80, v236, v80
	v_exp_f32_e32 v248, v85
	s_waitcnt lgkmcnt(1)
	v_mfma_f32_32x32x16_bf16 v[96:111], v[146:149], v[116:119], v[96:111]
	v_add_f32_e32 v80, v237, v80
	v_exp_f32_e32 v249, v86
	v_add_f32_e32 v80, v238, v80
	v_exp_f32_e32 v252, v87
	s_waitcnt lgkmcnt(0)
	v_mfma_f32_32x32x16_bf16 v[64:79], v[150:153], v[116:119], v[64:79]
	ds_read_b128 v[146:149], v190 offset:0
	ds_read_b128 v[150:153], v190 offset:8192
	v_add_f32_e32 v80, v239, v80
	v_add_f32_e32 v80, v247, v80
	v_add_f32_e32 v80, v248, v80
	v_add_f32_e32 v80, v249, v80
	v_add_f32_e32 v80, v252, v80
	v_add_f32_e32 v80, v154, v80
	s_waitcnt lgkmcnt(1)
	v_mfma_f32_32x32x16_bf16 v[96:111], v[146:149], v[120:123], v[96:111]
	v_add_f32_e32 v80, v155, v80
	v_add_f32_e32 v80, v156, v80
	v_add_f32_e32 v80, v157, v80
	v_add_f32_e32 v80, v158, v80
	v_add_f32_e32 v80, v159, v80
	s_waitcnt lgkmcnt(0)
; #define SBAR() __builtin_amdgcn_sched_barrier(0)
; #define SLOAD(i, k0) do { sr_[i].vs0 = ld8(&Vh[(long)((k0) + sr) * LDK + sc]); sr_[i].vs1 = ld8(&Vh[(long)((k0) + 32 + sr) * LDK + sc]); \
;     sr_[i].ks0 = ld8(&Kh[(long)((k0) + sr) * LDK + sc]); sr_[i].ks1 = ld8(&Kh[(long)((k0) + 32 + sr) * LDK + sc]); } while (0)
; #define SWAIT() asm volatile("s_waitcnt vmcnt(4)" ::: "memory")
; #define NOP_() do { } while (0)
; template <int D0, int BOFF> __device__ __forceinline__ void pv_one_i(f32x16& od, int vb, bf16x8 pa0, bf16x8 pa1, bf16x8 pa2, bf16x8 pa3) {
;   const s16x4 l0 = tr_read<BOFF + v_rd_off(D0, 0, 0)>(vb), h0 = tr_read<BOFF + v_rd_off(D0, 0, 1)>(vb), l1 = tr_read<BOFF + v_rd_off(D0, 1, 0)>(vb), h1 = tr_read<BOFF + v_rd_off(D0, 1, 1)>(vb);
;   const s16x4 l2 = tr_read<BOFF + v_rd_off(D0, 2, 0)>(vb), h2 = tr_read<BOFF + v_rd_off(D0, 2, 1)>(vb), l3 = tr_read<BOFF + v_rd_off(D0, 3, 0)>(vb), h3 = tr_read<BOFF + v_rd_off(D0, 3, 1)>(vb);
;   asm volatile("s_waitcnt lgkmcnt(0)" ::: "memory"); SBAR();
;     ...
;   od = __builtin_amdgcn_mfma_f32_32x32x16_bf16(pa0, PK(l0, h0), od, 0, 0, 0);
;   od = __builtin_amdgcn_mfma_f32_32x32x16_bf16(pa1, PK(l1, h1), od, 0, 0, 0);
;   od = __builtin_amdgcn_mfma_f32_32x32x16_bf16(pa2, PK(l2, h2), od, 0, 0, 0);
;   od = __builtin_amdgcn_mfma_f32_32x32x16_bf16(pa3, PK(l3, h3), od, 0, 0, 0);
;     ...
; }
; template <int BOFF> __device__ __forceinline__ void pv_i(f32x16* o, int vb, bf16x8 pa0, bf16x8 pa1, bf16x8 pa2, bf16x8 pa3) {
;   pv_one_i<0, BOFF>(o[0], vb, pa0, pa1, pa2, pa3); pv_one_i<1, BOFF>(o[1], vb, pa0, pa1, pa2, pa3); pv_one_i<2, BOFF>(o[2], vb, pa0, pa1, pa2, pa3); pv_one_i<3, BOFF>(o[3], vb, pa0, pa1, pa2, pa3);
; }
; template <bool PARTIAL, bool FIXED> ...
;     ...
;   int j = 1;
;   for (; j + 6 < NT; j += 6) {
;     HALF_B(1, 0, SLOAD(1, (j + 2) * KVBLK), do { SWAIT(); SWRITE_I(2, 0); } while (0));
;     HALF_A(2, 1, NOP_(), SLOAD(0, (j + 3) * KVBLK), do { SWAIT(); SWRITE_I(0, 1); } while (0));
;     HALF_B(0, 2, SLOAD(1, (j + 4) * KVBLK), do { SWAIT(); SWRITE_I(1, 0); } while (0));
;     HALF_A(1, 0, NOP_(), SLOAD(0, (j + 5) * KVBLK), do { SWAIT(); SWRITE_I(2, 1); } while (0));
;     HALF_B(2, 1, SLOAD(1, (j + 6) * KVBLK), do { SWAIT(); SWRITE_I(0, 0); } while (0));
;     HALF_A(0, 2, NOP_(), SLOAD(0, (j + 7) * KVBLK), do { SWAIT(); SWRITE_I(1, 1); } while (0));
	v_mfma_f32_32x32x16_bf16 v[64:79], v[150:153], v[120:123], v[64:79]
	ds_read_b128 v[146:149], v191 offset:0
	ds_read_b128 v[150:153], v191 offset:8192
	v_add_f32_e32 v80, v160, v80
	v_add_f32_e32 v80, v95, v80
	v_mov_b32_e32 v81, v80
	s_nop 1
	v_permlane32_swap_b32_e32 v80, v81
	v_add_f32_e32 v80, v80, v81
	s_waitcnt lgkmcnt(1)
	v_mfma_f32_32x32x16_bf16 v[96:111], v[146:149], v[124:127], v[96:111]
	v_add_f32_e32 v215, v128, v80
	v_cvt_pk_bf16_f32 v80, v180, v181
	v_cvt_pk_bf16_f32 v81, v182, v183
	v_cvt_pk_bf16_f32 v82, v184, v185
	v_cvt_pk_bf16_f32 v83, v186, v187
	s_waitcnt lgkmcnt(0)
	v_mfma_f32_32x32x16_bf16 v[64:79], v[150:153], v[124:127], v[64:79]
	ds_read_b128 v[146:149], v192 offset:0
	ds_read_b128 v[150:153], v192 offset:8192
	v_cvt_pk_bf16_f32 v84, v188, v189
	v_cvt_pk_bf16_f32 v85, v196, v197
	v_cvt_pk_bf16_f32 v86, v198, v199
	v_cvt_pk_bf16_f32 v87, v216, v217
	v_cvt_pk_bf16_f32 v88, v236, v237
	v_cvt_pk_bf16_f32 v89, v238, v239
	s_waitcnt lgkmcnt(1)
	v_mfma_f32_32x32x16_bf16 v[96:111], v[146:149], v[130:133], v[96:111]
	v_cvt_pk_bf16_f32 v90, v247, v248
	v_cvt_pk_bf16_f32 v91, v249, v252
	v_cvt_pk_bf16_f32 v92, v154, v155
	v_cvt_pk_bf16_f32 v93, v156, v157
	v_cvt_pk_bf16_f32 v94, v158, v159
	s_waitcnt lgkmcnt(0)
	v_mfma_f32_32x32x16_bf16 v[64:79], v[150:153], v[130:133], v[64:79]
	ds_read_b128 v[146:149], v193 offset:0
	ds_read_b128 v[150:153], v193 offset:8192
	ds_read_b64_tr_b16 v[180:181], v206 offset:0x8000
	ds_read_b64_tr_b16 v[182:183], v206 offset:0x8800
	ds_read_b64_tr_b16 v[184:185], v206 offset:0x9000
	ds_read_b64_tr_b16 v[186:187], v206 offset:0x9800
	ds_read_b64_tr_b16 v[216:217], v206 offset:0xa000
	ds_read_b64_tr_b16 v[218:219], v206 offset:0xa800
	ds_read_b64_tr_b16 v[220:221], v206 offset:0xb000
	ds_read_b64_tr_b16 v[222:223], v206 offset:0xb800
	v_cvt_pk_bf16_f32 v95, v160, v95
	s_nop 0
	v_permlane32_swap_b32_e32 v80, v82
	v_permlane32_swap_b32_e32 v81, v83
	v_permlane32_swap_b32_e32 v84, v86
	v_permlane32_swap_b32_e32 v85, v87
	s_waitcnt lgkmcnt(9)
	v_mfma_f32_32x32x16_bf16 v[96:111], v[146:149], v[134:137], v[96:111]
	v_permlane32_swap_b32_e32 v88, v90
	v_permlane32_swap_b32_e32 v89, v91
	v_permlane32_swap_b32_e32 v92, v94
	v_permlane32_swap_b32_e32 v93, v95
	s_waitcnt lgkmcnt(8)
	v_mfma_f32_32x32x16_bf16 v[64:79], v[150:153], v[134:137], v[64:79]
	s_waitcnt vmcnt(0)
	ds_write_b128 v211, v[162:165] offset:16384
	s_nop 0
	s_waitcnt lgkmcnt(7)
	v_mfma_f32_32x32x16_bf16 v[0:15], v[80:83], v[180:183], v[0:15]
	ds_read_b64_tr_b16 v[180:181], v206 offset:0x8200
	ds_read_b64_tr_b16 v[182:183], v206 offset:0x8a00
	v_add_co_u32_e32 v150, vcc, s58, v178
	s_nop 1
	v_addc_co_u32_e32 v151, vcc, -1, v179, vcc
	s_waitcnt lgkmcnt(7)
	v_mfma_f32_32x32x16_bf16 v[0:15], v[84:87], v[184:187], v[0:15]
	ds_read_b64_tr_b16 v[184:185], v206 offset:0x9200
	ds_read_b64_tr_b16 v[186:187], v206 offset:0x9a00
	global_load_dwordx4 v[146:149], v[150:151], off
	global_load_dwordx4 v[154:157], v[150:151], off offset:-512
	s_nop 0
	global_load_dwordx4 v[150:153], v[178:179], off
	global_load_dwordx4 v[158:161], v[178:179], off offset:-512
	s_waitcnt lgkmcnt(7)
	v_mfma_f32_32x32x16_bf16 v[0:15], v[88:91], v[216:219], v[0:15]
	ds_read_b64_tr_b16 v[216:217], v206 offset:0xa200
	ds_read_b64_tr_b16 v[218:219], v206 offset:0xaa00
	s_waitcnt lgkmcnt(7)
	v_mfma_f32_32x32x16_bf16 v[0:15], v[92:95], v[220:223], v[0:15]
	ds_read_b64_tr_b16 v[220:221], v206 offset:0xb200
	ds_read_b64_tr_b16 v[222:223], v206 offset:0xba00
	ds_write_b128 v212, v[174:177] offset:16384
	s_waitcnt lgkmcnt(7)
	v_mfma_f32_32x32x16_bf16 v[16:31], v[80:83], v[180:183], v[16:31]
	ds_read_b64_tr_b16 v[180:181], v206 offset:0x8400
	ds_read_b64_tr_b16 v[182:183], v206 offset:0x8c00
	s_waitcnt lgkmcnt(7)
	v_mfma_f32_32x32x16_bf16 v[16:31], v[84:87], v[184:187], v[16:31]
	ds_read_b64_tr_b16 v[184:185], v206 offset:0x9400
	ds_read_b64_tr_b16 v[186:187], v206 offset:0x9c00
	s_waitcnt lgkmcnt(7)
	v_mfma_f32_32x32x16_bf16 v[16:31], v[88:91], v[216:219], v[16:31]
	ds_read_b64_tr_b16 v[216:217], v206 offset:0xa400
	ds_read_b64_tr_b16 v[218:219], v206 offset:0xac00
	s_waitcnt lgkmcnt(7)
	v_mfma_f32_32x32x16_bf16 v[16:31], v[92:95], v[220:223], v[16:31]
	ds_read_b64_tr_b16 v[220:221], v206 offset:0xb400
	ds_read_b64_tr_b16 v[222:223], v206 offset:0xbc00
	ds_write_b128 v213, v[166:169] offset:16384
	s_waitcnt lgkmcnt(7)
	v_mfma_f32_32x32x16_bf16 v[32:47], v[80:83], v[180:183], v[32:47]
	ds_read_b64_tr_b16 v[180:181], v206 offset:0x8600
	ds_read_b64_tr_b16 v[182:183], v206 offset:0x8e00
	v_exp_f32_e32 v229, v96
	v_exp_f32_e32 v243, v97
	s_waitcnt lgkmcnt(7)
	v_mfma_f32_32x32x16_bf16 v[32:47], v[84:87], v[184:187], v[32:47]
	ds_read_b64_tr_b16 v[184:185], v206 offset:0x9600
	ds_read_b64_tr_b16 v[186:187], v206 offset:0x9e00
	v_exp_f32_e32 v244, v98
	v_exp_f32_e32 v246, v99
	s_waitcnt lgkmcnt(7)
	v_mfma_f32_32x32x16_bf16 v[32:47], v[88:91], v[216:219], v[32:47]
	ds_read_b64_tr_b16 v[216:217], v206 offset:0xa600
	ds_read_b64_tr_b16 v[218:219], v206 offset:0xae00
	v_exp_f32_e32 v242, v100
	v_exp_f32_e32 v245, v101
	s_waitcnt lgkmcnt(7)
	v_mfma_f32_32x32x16_bf16 v[32:47], v[92:95], v[220:223], v[32:47]
	ds_read_b64_tr_b16 v[220:221], v206 offset:0xb600
	ds_read_b64_tr_b16 v[222:223], v206 offset:0xbe00
	v_exp_f32_e32 v227, v102
	v_exp_f32_e32 v228, v103
	ds_write_b128 v214, v[170:173] offset:16384
	s_waitcnt lgkmcnt(7)
	v_mfma_f32_32x32x16_bf16 v[48:63], v[80:83], v[180:183], v[48:63]
	s_waitcnt lgkmcnt(5)
	v_mfma_f32_32x32x16_bf16 v[48:63], v[84:87], v[184:187], v[48:63]
	v_exp_f32_e32 v226, v105
	v_exp_f32_e32 v224, v106
	v_exp_f32_e32 v225, v107
	s_waitcnt vmcnt(4)
	s_add_i32 s28, s28, 6
	v_lshl_add_u64 v[178:179], v[178:179], 0, s[60:61]
	s_waitcnt lgkmcnt(3)
	v_mfma_f32_32x32x16_bf16 v[48:63], v[88:91], v[216:219], v[48:63]
	v_exp_f32_e32 v219, v110
	s_cmpk_lt_u32 s28, 0x75
	s_waitcnt lgkmcnt(1)
	v_mfma_f32_32x32x16_bf16 v[48:63], v[92:95], v[220:223], v[48:63]
	v_exp_f32_e32 v223, v104
	v_exp_f32_e32 v220, v108
	v_exp_f32_e32 v222, v109
	v_exp_f32_e32 v221, v111
	s_cbranch_scc1 .LBB0_352
; #define NOP_() do { } while (0)
; __device__ __forceinline__ void finishSM(f32x16& p0, f32x16& p1, float alpha, float& l_reg, bf16x8& pa0, bf16x8& pa1, bf16x8& pa2, bf16x8& pa3) {
;   for (int r = 0; r < 16; ++r) p1[r] = __builtin_amdgcn_exp2f(p1[r]);
;   float ps = 0; for (int r = 0; r < 16; ++r) ps += p0[r]; for (int r = 0; r < 16; ++r) ps += p1[r];
;   { auto rr = __builtin_amdgcn_permlane32_swap(__float_as_uint(ps), __float_as_uint(ps), false, false);
;     ps = __uint_as_float(rr[0]) + __uint_as_float(rr[1]); }
;   l_reg = l_reg * alpha + ps;
;     ...
;   PK4(p0, 0, pa0); PK4(p0, 8, pa1); PK4(p1, 0, pa2); PK4(p1, 8, pa3);
;     ...
; }
; __device__ __forceinline__ void qkt(f32x16& p0, f32x16& p1, const bf16* Ks, const bf16x8* qr, int r32, int hi) {
;   p0 = f32x16{}; p1 = f32x16{};
;   for (int d0 = 0; d0 < 8; ++d0) { int cb = (d0 * 16 + hi * 8) * 2;
;     bf16x8 b0 = *reinterpret_cast<const bf16x8*>((const char*)Ks + KSWZ(r32, cb));
;     bf16x8 b1 = *reinterpret_cast<const bf16x8*>((const char*)Ks + KSWZ(32 + r32, cb));
;     p0 = __builtin_amdgcn_mfma_f32_32x32x16_bf16(b0, qr[d0], p0, 0, 0, 0);
;     p1 = __builtin_amdgcn_mfma_f32_32x32x16_bf16(b1, qr[d0], p1, 0, 0, 0); }
; }
; __device__ __forceinline__ int v_st(int k, int c) { const int kk = (k & ~0xC) | ((k & 4) << 1) | ((k & 8) >> 1); return ((kk >> 3) * 4 + (c >> 5)) * 512 + ((kk & 7) * 32 + (c & 31)) * 2; }
; __device__ __forceinline__ int v_rd_base(int lane) { return ((lane & 3) << 3) | (((lane >> 2) & 3) << 6) | (((lane >> 4) & 1) << 5) | (((lane >> 5) & 1) << 8); }
; template <int OFF> __device__ __forceinline__ s16x4 tr_read(int vb) {
;   s16x4 r; asm volatile("ds_read_b64_tr_b16 %0, %1 offset:%2" : "=&v"(r) : "v"(vb), "i"(OFF) : "memory"); return r;
; }
; template <int D0> __device__ __forceinline__ void pv_one(f32x16& od, int vb, bf16x8 pa0, bf16x8 pa1, bf16x8 pa2, bf16x8 pa3) {
;   const s16x4 l0 = tr_read<v_rd_off(D0, 0, 0)>(vb), h0 = tr_read<v_rd_off(D0, 0, 1)>(vb), l1 = tr_read<v_rd_off(D0, 1, 0)>(vb), h1 = tr_read<v_rd_off(D0, 1, 1)>(vb);
; template <bool PARTIAL, bool FIXED> ...
;     ...
;   if constexpr (!PARTIAL) { const int i1 = tid & 255;
;     warm0 = *(const unsigned*)(Qb_n + (long)(tid >> 1) * LDQ + (tid & 1) * 64);
;     warm1 = *(const unsigned*)((tid < 256 ? Kh_n : Vh_n) + (long)(i1 >> 1) * LDK + (i1 & 1) * 64); }
;   HALF_B(1, 0, NOP_(), SWRITE_I(2, 0));
	v_mov_b32_e32 v252, 0x7fc00000
	v_readlane_b32 s8, v255, 42
	v_readlane_b32 s9, v255, 43
	s_add_u32 s2, s8, s6
	s_addc_u32 s3, s9, s7
	s_lshl_b32 s4, s65, 1
	s_add_u32 s2, s2, s4
	s_addc_u32 s3, s3, 0
	v_ashrrev_i32_e32 v82, 1, v195
	v_mov_b64_e32 v[80:81], s[2:3]
	v_mad_i64_i32 v[80:81], s[2:3], v82, s17, v[80:81]
	v_lshlrev_b32_e32 v82, 7, v195
	v_and_b32_e32 v128, 0x80, v82
	v_lshl_add_u64 v[80:81], v[80:81], 0, v[128:129]
	s_add_u32 s4, s8, s64
	global_load_dword v216, v[80:81], off
	v_cmp_gt_i32_e32 vcc, s14, v195
	v_mov_b32_e32 v80, 0xa00
	v_mov_b32_e32 v81, 0x800
	s_addc_u32 s5, s9, s57
	v_cndmask_b32_e32 v80, v80, v81, vcc
	v_mov_b32_e32 v81, v129
	v_bfe_u32 v82, v195, 1, 7
	v_lshl_add_u64 v[80:81], s[4:5], 0, v[80:81]
	s_lshl_b32 s46, s56, 1
	v_mul_u32_u24_e32 v82, 0x600, v82
	v_lshl_add_u64 v[80:81], v[80:81], 0, s[46:47]
	v_lshlrev_b32_e32 v82, 1, v82
	v_mov_b32_e32 v83, v129
	v_lshl_add_u64 v[80:81], v[80:81], 0, v[82:83]
	v_lshl_add_u64 v[80:81], v[80:81], 0, v[128:129]
	global_load_dword v217, v[80:81], off
	v_and_b32_e32 v247, 0x3fffffc0, v195
	s_waitcnt lgkmcnt(0)
	s_barrier
	ds_read_b128 v[80:83], v207 offset:16384
	ds_read_b128 v[96:99], v207 offset:24576
	ds_read_b128 v[100:103], v208 offset:16384
	ds_read_b128 v[170:173], v208 offset:24576
	v_exp_f32_e32 v104, v68
	v_exp_f32_e32 v105, v69
	s_waitcnt lgkmcnt(3)
	v_mfma_f32_32x32x16_bf16 v[80:95], v[80:83], v[142:145], 0
	v_exp_f32_e32 v106, v70
	v_exp_f32_e32 v107, v71
	v_exp_f32_e32 v108, v72
	v_exp_f32_e32 v109, v73
	v_exp_f32_e32 v110, v74
	v_exp_f32_e32 v111, v75
	v_exp_f32_e32 v196, v76
	s_waitcnt lgkmcnt(1)
	v_mfma_f32_32x32x16_bf16 v[80:95], v[100:103], v[138:141], v[80:95]
	ds_read_b128 v[100:103], v209 offset:16384
	ds_read_b128 v[162:165], v209 offset:24576
	v_exp_f32_e32 v197, v77
	v_exp_f32_e32 v198, v78
	v_exp_f32_e32 v79, v79
	s_waitcnt lgkmcnt(1)
	v_mfma_f32_32x32x16_bf16 v[80:95], v[100:103], v[112:115], v[80:95]
	ds_read_b128 v[100:103], v210 offset:16384
	ds_read_b128 v[166:169], v210 offset:24576
	s_waitcnt lgkmcnt(1)
	v_mfma_f32_32x32x16_bf16 v[80:95], v[100:103], v[116:119], v[80:95]
	ds_read_b128 v[100:103], v190 offset:16384
	ds_read_b128 v[174:177], v190 offset:24576
	s_waitcnt lgkmcnt(1)
	v_mfma_f32_32x32x16_bf16 v[80:95], v[100:103], v[120:123], v[80:95]
	ds_read_b128 v[100:103], v191 offset:16384
	ds_read_b128 v[178:181], v191 offset:24576
	s_waitcnt lgkmcnt(1)
	v_mfma_f32_32x32x16_bf16 v[80:95], v[100:103], v[124:127], v[80:95]
	ds_read_b128 v[100:103], v192 offset:16384
	ds_read_b128 v[182:185], v192 offset:24576
	s_waitcnt lgkmcnt(1)
	v_mfma_f32_32x32x16_bf16 v[80:95], v[100:103], v[130:133], v[80:95]
	ds_read_b128 v[100:103], v193 offset:16384
	ds_read_b128 v[186:189], v193 offset:24576
	s_waitcnt lgkmcnt(1)
	v_mfma_f32_32x32x16_bf16 v[80:95], v[100:103], v[134:137], v[80:95]
	v_exp_f32_e32 v100, v64
	v_add_f32_e32 v64, 0, v229
	v_add_f32_e32 v64, v243, v64
	v_add_f32_e32 v64, v244, v64
	v_add_f32_e32 v64, v246, v64
	v_add_f32_e32 v64, v242, v64
	v_add_f32_e32 v64, v245, v64
	v_add_f32_e32 v64, v227, v64
	v_add_f32_e32 v64, v228, v64
	v_add_f32_e32 v64, v223, v64
	v_add_f32_e32 v64, v226, v64
	v_add_f32_e32 v64, v224, v64
	v_add_f32_e32 v64, v225, v64
	v_add_f32_e32 v64, v220, v64
	v_exp_f32_e32 v101, v65
	v_add_f32_e32 v64, v222, v64
	v_exp_f32_e32 v102, v66
	v_add_f32_e32 v64, v219, v64
	v_exp_f32_e32 v103, v67
	v_add_f32_e32 v64, v221, v64
	v_add_f32_e32 v64, v100, v64
	v_add_f32_e32 v64, v101, v64
	v_add_f32_e32 v64, v102, v64
	v_add_f32_e32 v64, v103, v64
	v_add_f32_e32 v64, v104, v64
	v_add_f32_e32 v64, v105, v64
	v_add_f32_e32 v64, v106, v64
	v_add_f32_e32 v64, v107, v64
	v_add_f32_e32 v64, v108, v64
	v_add_f32_e32 v64, v109, v64
	v_add_f32_e32 v64, v110, v64
	v_add_f32_e32 v64, v111, v64
	v_add_f32_e32 v64, v196, v64
	v_add_f32_e32 v64, v197, v64
	v_add_f32_e32 v64, v198, v64
	v_add_f32_e32 v128, v79, v64
	v_mov_b32_e32 v218, v128
	s_nop 1
	v_permlane32_swap_b32_e32 v128, v218
	v_cvt_pk_bf16_f32 v64, v229, v243
	v_cvt_pk_bf16_f32 v65, v244, v246
	v_cvt_pk_bf16_f32 v66, v242, v245
	v_cvt_pk_bf16_f32 v67, v227, v228
	v_cvt_pk_bf16_f32 v68, v223, v226
	v_cvt_pk_bf16_f32 v69, v224, v225
	v_cvt_pk_bf16_f32 v70, v220, v222
	v_cvt_pk_bf16_f32 v71, v219, v221
	v_cvt_pk_bf16_f32 v72, v100, v101
	v_cvt_pk_bf16_f32 v73, v102, v103
	v_cvt_pk_bf16_f32 v74, v104, v105
	v_cvt_pk_bf16_f32 v75, v106, v107
	v_cvt_pk_bf16_f32 v76, v108, v109
	v_cvt_pk_bf16_f32 v77, v110, v111
	v_cvt_pk_bf16_f32 v78, v196, v197
	v_cvt_pk_bf16_f32 v79, v198, v79
	s_nop 0
	v_permlane32_swap_b32_e32 v64, v66
	v_permlane32_swap_b32_e32 v65, v67
	v_permlane32_swap_b32_e32 v68, v70
	v_permlane32_swap_b32_e32 v69, v71
	v_permlane32_swap_b32_e32 v72, v74
	v_permlane32_swap_b32_e32 v73, v75
	v_permlane32_swap_b32_e32 v76, v78
	v_permlane32_swap_b32_e32 v77, v79
	ds_read_b64_tr_b16 v[100:101], v206 offset:0
	ds_read_b64_tr_b16 v[102:103], v206 offset:0x800
	ds_read_b64_tr_b16 v[104:105], v206 offset:0x1000
	ds_read_b64_tr_b16 v[106:107], v206 offset:0x1800
	ds_read_b64_tr_b16 v[108:109], v206 offset:0x2000
	ds_read_b64_tr_b16 v[110:111], v206 offset:0x2800
	ds_read_b64_tr_b16 v[220:221], v206 offset:0x3000
	ds_read_b64_tr_b16 v[222:223], v206 offset:0x3800
	s_waitcnt lgkmcnt(0)
	s_nop 0
	v_mfma_f32_32x32x16_bf16 v[0:15], v[64:67], v[100:103], v[0:15]
	ds_read_b64_tr_b16 v[100:101], v206 offset:0x200
	ds_read_b64_tr_b16 v[102:103], v206 offset:0xa00
	v_mfma_f32_32x32x16_bf16 v[0:15], v[68:71], v[104:107], v[0:15]
	ds_read_b64_tr_b16 v[104:105], v206 offset:0x1200
	ds_read_b64_tr_b16 v[106:107], v206 offset:0x1a00
	v_mfma_f32_32x32x16_bf16 v[0:15], v[72:75], v[108:111], v[0:15]
	ds_read_b64_tr_b16 v[108:109], v206 offset:0x2200
	ds_read_b64_tr_b16 v[110:111], v206 offset:0x2a00
	v_mfma_f32_32x32x16_bf16 v[0:15], v[76:79], v[220:223], v[0:15]
	ds_read_b64_tr_b16 v[220:221], v206 offset:0x3200
	ds_read_b64_tr_b16 v[222:223], v206 offset:0x3a00
	s_waitcnt lgkmcnt(0)
; #define SBAR() __builtin_amdgcn_sched_barrier(0)
; #define SWRITE_I(B, i) do { LDSV(wv0 + (B) * 16384) = sr_[i].vs0; LDSV(wv1 + (B) * 16384) = sr_[i].vs1; LDSV(wk0 + (B) * 16384) = sr_[i].ks0; LDSV(wk1 + (B) * 16384) = sr_[i].ks1; } while (0)
; #define NOP_() do { } while (0)
; template <int BOFF> __device__ __forceinline__ void qkt_i(f32x16& p0, f32x16& p1, const int (&kb)[4], const bf16x8* qr) {
;   p0 = f32x16{}; p1 = f32x16{};
; #pragma unroll
;   for (int d0 = 0; d0 < 8; ++d0) { const int off = BOFF + (d0 >> 2) * 128;
;     const bf16x8 b0 = LDSV(kb[d0 & 3] + off), b1 = LDSV(kb[d0 & 3] + off + 8192);
;     p0 = __builtin_amdgcn_mfma_f32_32x32x16_bf16(b0, qr[d0], p0, 0, 0, 0);
;     p1 = __builtin_amdgcn_mfma_f32_32x32x16_bf16(b1, qr[d0], p1, 0, 0, 0); }
; }
; template <int D0, int BOFF> __device__ __forceinline__ void pv_one_i(f32x16& od, int vb, bf16x8 pa0, bf16x8 pa1, bf16x8 pa2, bf16x8 pa3) {
;   const s16x4 l0 = tr_read<BOFF + v_rd_off(D0, 0, 0)>(vb), h0 = tr_read<BOFF + v_rd_off(D0, 0, 1)>(vb), l1 = tr_read<BOFF + v_rd_off(D0, 1, 0)>(vb), h1 = tr_read<BOFF + v_rd_off(D0, 1, 1)>(vb);
;   const s16x4 l2 = tr_read<BOFF + v_rd_off(D0, 2, 0)>(vb), h2 = tr_read<BOFF + v_rd_off(D0, 2, 1)>(vb), l3 = tr_read<BOFF + v_rd_off(D0, 3, 0)>(vb), h3 = tr_read<BOFF + v_rd_off(D0, 3, 1)>(vb);
;   asm volatile("s_waitcnt lgkmcnt(0)" ::: "memory"); SBAR();
;     ...
;   od = __builtin_amdgcn_mfma_f32_32x32x16_bf16(pa0, PK(l0, h0), od, 0, 0, 0);
;   od = __builtin_amdgcn_mfma_f32_32x32x16_bf16(pa1, PK(l1, h1), od, 0, 0, 0);
;   od = __builtin_amdgcn_mfma_f32_32x32x16_bf16(pa2, PK(l2, h2), od, 0, 0, 0);
;   od = __builtin_amdgcn_mfma_f32_32x32x16_bf16(pa3, PK(l3, h3), od, 0, 0, 0);
;     ...
; }
; template <int BOFF> __device__ __forceinline__ void pv_i(f32x16* o, int vb, bf16x8 pa0, bf16x8 pa1, bf16x8 pa2, bf16x8 pa3) {
;   pv_one_i<0, BOFF>(o[0], vb, pa0, pa1, pa2, pa3); pv_one_i<1, BOFF>(o[1], vb, pa0, pa1, pa2, pa3); pv_one_i<2, BOFF>(o[2], vb, pa0, pa1, pa2, pa3); pv_one_i<3, BOFF>(o[3], vb, pa0, pa1, pa2, pa3);
; }
; template <bool PARTIAL, bool FIXED> ...
;     ...
;   HALF_B(1, 0, NOP_(), SWRITE_I(2, 0));
;   HALF_A(2, 1, do { if (mask_last) { asm volatile("; masked tail tile" ::: "memory"); const float NEG = -INFINITY; \
;       _Pragma("unroll") for (int r = 8; r < 16; ++r) pA0[r] = NEG; _Pragma("unroll") for (int r = 0; r < 16; ++r) pA1[r] = NEG; } } while (0), NOP_(), NOP_());
	v_mfma_f32_32x32x16_bf16 v[16:31], v[64:67], v[100:103], v[16:31]
	ds_read_b64_tr_b16 v[100:101], v206 offset:0x400
	ds_read_b64_tr_b16 v[102:103], v206 offset:0xc00
	v_mfma_f32_32x32x16_bf16 v[16:31], v[68:71], v[104:107], v[16:31]
	ds_read_b64_tr_b16 v[104:105], v206 offset:0x1400
	ds_read_b64_tr_b16 v[106:107], v206 offset:0x1c00
	v_mfma_f32_32x32x16_bf16 v[16:31], v[72:75], v[108:111], v[16:31]
	ds_read_b64_tr_b16 v[108:109], v206 offset:0x2400
	ds_read_b64_tr_b16 v[110:111], v206 offset:0x2c00
	v_mfma_f32_32x32x16_bf16 v[16:31], v[76:79], v[220:223], v[16:31]
	ds_read_b64_tr_b16 v[220:221], v206 offset:0x3400
	ds_read_b64_tr_b16 v[222:223], v206 offset:0x3c00
	s_waitcnt lgkmcnt(0)
	v_mfma_f32_32x32x16_bf16 v[32:47], v[64:67], v[100:103], v[32:47]
	ds_read_b64_tr_b16 v[100:101], v206 offset:0x600
	ds_read_b64_tr_b16 v[102:103], v206 offset:0xe00
	v_mfma_f32_32x32x16_bf16 v[32:47], v[68:71], v[104:107], v[32:47]
	ds_read_b64_tr_b16 v[104:105], v206 offset:0x1600
	ds_read_b64_tr_b16 v[106:107], v206 offset:0x1e00
	v_mfma_f32_32x32x16_bf16 v[32:47], v[72:75], v[108:111], v[32:47]
	ds_read_b64_tr_b16 v[108:109], v206 offset:0x2600
	ds_read_b64_tr_b16 v[110:111], v206 offset:0x2e00
	v_mfma_f32_32x32x16_bf16 v[32:47], v[76:79], v[220:223], v[32:47]
	ds_read_b64_tr_b16 v[220:221], v206 offset:0x3600
	ds_read_b64_tr_b16 v[222:223], v206 offset:0x3e00
	s_waitcnt lgkmcnt(0)
	v_mfma_f32_32x32x16_bf16 v[48:63], v[64:67], v[100:103], v[48:63]
	s_waitcnt vmcnt(5)
	ds_write_b128 v211, v[146:149] offset:32768
	s_waitcnt vmcnt(3)
	ds_write_b128 v212, v[150:153] offset:32768
	ds_write_b128 v213, v[154:157] offset:32768
	s_waitcnt vmcnt(2)
	ds_write_b128 v214, v[158:161] offset:32768
	s_waitcnt lgkmcnt(0)
	s_barrier
	v_mfma_f32_32x32x16_bf16 v[48:63], v[68:71], v[104:107], v[48:63]
	v_mfma_f32_32x32x16_bf16 v[48:63], v[72:75], v[108:111], v[48:63]
	v_mfma_f32_32x32x16_bf16 v[48:63], v[76:79], v[220:223], v[48:63]
	ds_read_b128 v[64:67], v207 offset:32768
	ds_read_b128 v[100:103], v208 offset:32768
	s_add_i32 s2, 0, 0x18000
	s_waitcnt lgkmcnt(1)
	v_mfma_f32_32x32x16_bf16 v[64:79], v[64:67], v[142:145], 0
	s_waitcnt lgkmcnt(0)
	v_mfma_f32_32x32x16_bf16 v[64:79], v[100:103], v[138:141], v[64:79]
	ds_read_b128 v[100:103], v209 offset:32768
	s_waitcnt lgkmcnt(0)
	v_mfma_f32_32x32x16_bf16 v[64:79], v[100:103], v[112:115], v[64:79]
	ds_read_b128 v[100:103], v210 offset:32768
	s_waitcnt lgkmcnt(0)
	v_mfma_f32_32x32x16_bf16 v[64:79], v[100:103], v[116:119], v[64:79]
	ds_read_b128 v[100:103], v190 offset:32768
	s_waitcnt lgkmcnt(0)
	v_mfma_f32_32x32x16_bf16 v[64:79], v[100:103], v[120:123], v[64:79]
	ds_read_b128 v[100:103], v191 offset:32768
	s_waitcnt lgkmcnt(0)
	v_mfma_f32_32x32x16_bf16 v[64:79], v[100:103], v[124:127], v[64:79]
	ds_read_b128 v[100:103], v192 offset:32768
	s_waitcnt lgkmcnt(0)
	v_mfma_f32_32x32x16_bf16 v[64:79], v[100:103], v[130:133], v[64:79]
	ds_read_b128 v[100:103], v193 offset:32768
	s_waitcnt lgkmcnt(0)
	v_and_b32_e32 v190, 63, v195
	v_lshlrev_b32_e32 v191, 4, v195
	v_and_b32_e32 v192, 31, v195
	v_bfe_u32 v193, v195, 5, 1
	v_mfma_f32_32x32x16_bf16 v[64:79], v[100:103], v[134:137], v[64:79]
	v_mfma_f32_32x32x16_bf16 v[96:111], v[96:99], v[142:145], 0
	s_nop 10
	v_exp_f32_e32 v72, v80
	v_exp_f32_e32 v80, v81
	v_exp_f32_e32 v73, v82
	v_exp_f32_e32 v81, v83
	v_exp_f32_e32 v74, v84
	v_add_f32_e32 v84, 0, v72
	v_exp_f32_e32 v82, v85
	v_mfma_f32_32x32x16_bf16 v[96:111], v[170:173], v[138:141], v[96:111]
	v_add_f32_e32 v84, v80, v84
	v_exp_f32_e32 v75, v86
	v_add_f32_e32 v84, v73, v84
	v_exp_f32_e32 v83, v87
	v_add_f32_e32 v84, v81, v84
	v_exp_f32_e32 v76, v88
	v_add_f32_e32 v84, v74, v84
	v_mfma_f32_32x32x16_bf16 v[96:111], v[162:165], v[112:115], v[96:111]
	v_exp_f32_e32 v85, v89
	v_add_f32_e32 v84, v82, v84
	v_exp_f32_e32 v77, v90
	v_add_f32_e32 v84, v75, v84
	v_exp_f32_e32 v87, v91
	v_add_f32_e32 v84, v83, v84
	v_exp_f32_e32 v78, v92
	v_mfma_f32_32x32x16_bf16 v[96:111], v[166:169], v[116:119], v[96:111]
	v_add_f32_e32 v84, v76, v84
	v_exp_f32_e32 v89, v93
	v_add_f32_e32 v84, v85, v84
	v_exp_f32_e32 v79, v94
	v_add_f32_e32 v84, v77, v84
	v_exp_f32_e32 v90, v95
	v_add_f32_e32 v84, v87, v84
	v_mfma_f32_32x32x16_bf16 v[96:111], v[174:177], v[120:123], v[96:111]
	v_add_f32_e32 v84, v78, v84
	v_add_f32_e32 v84, v89, v84
	v_add_f32_e32 v84, v79, v84
	v_add_f32_e32 v84, v90, v84
	v_lshl_add_u32 v88, v247, 2, s2
	v_cvt_pk_bf16_f32 v72, v72, v80
	v_cvt_pk_bf16_f32 v73, v73, v81
	v_mfma_f32_32x32x16_bf16 v[96:111], v[178:181], v[124:127], v[96:111]
	v_cvt_pk_bf16_f32 v74, v74, v82
	v_cvt_pk_bf16_f32 v75, v75, v83
	v_cvt_pk_bf16_f32 v76, v76, v85
	v_cvt_pk_bf16_f32 v77, v77, v87
	v_cvt_pk_bf16_f32 v78, v78, v89
	v_cvt_pk_bf16_f32 v79, v79, v90
	s_nop 0
	v_permlane32_swap_b32_e32 v72, v74
	v_mfma_f32_32x32x16_bf16 v[96:111], v[182:185], v[130:133], v[96:111]
	v_permlane32_swap_b32_e32 v73, v75
	v_permlane32_swap_b32_e32 v76, v78
	v_permlane32_swap_b32_e32 v77, v79
	v_mfma_f32_32x32x16_bf16 v[96:111], v[186:189], v[134:137], v[96:111]
	s_nop 11
	v_exp_f32_e32 v91, v96
	v_exp_f32_e32 v92, v97
	v_exp_f32_e32 v93, v98
	v_exp_f32_e32 v94, v99
	v_exp_f32_e32 v95, v100
	v_add_f32_e32 v84, v84, v91
	v_exp_f32_e32 v96, v101
	v_add_f32_e32 v84, v92, v84
	v_exp_f32_e32 v97, v102
	v_add_f32_e32 v84, v93, v84
	v_exp_f32_e32 v98, v103
	v_add_f32_e32 v84, v94, v84
	v_exp_f32_e32 v99, v104
	v_add_f32_e32 v84, v95, v84
	v_exp_f32_e32 v100, v105
	v_add_f32_e32 v84, v96, v84
	v_exp_f32_e32 v101, v106
	v_add_f32_e32 v84, v97, v84
	v_exp_f32_e32 v102, v107
	v_add_f32_e32 v84, v98, v84
	v_exp_f32_e32 v103, v108
	v_add_f32_e32 v84, v99, v84
	v_exp_f32_e32 v104, v109
	v_add_f32_e32 v84, v100, v84
	v_exp_f32_e32 v105, v110
	v_add_f32_e32 v84, v101, v84
	v_exp_f32_e32 v106, v111
	v_add_f32_e32 v84, v102, v84
	v_add_f32_e32 v84, v103, v84
	v_add_f32_e32 v84, v104, v84
	v_add_f32_e32 v84, v105, v84
	v_add_f32_e32 v84, v106, v84
	v_mov_b32_e32 v86, v84
	s_nop 1
	v_permlane32_swap_b32_e32 v84, v86
	v_cvt_pk_bf16_f32 v80, v91, v92
	v_cvt_pk_bf16_f32 v81, v93, v94
	v_cvt_pk_bf16_f32 v82, v95, v96
	v_cvt_pk_bf16_f32 v83, v97, v98
	v_cvt_pk_bf16_f32 v90, v99, v100
	v_cvt_pk_bf16_f32 v91, v101, v102
	v_cvt_pk_bf16_f32 v92, v103, v104
	v_cvt_pk_bf16_f32 v93, v105, v106
	s_nop 0
	v_permlane32_swap_b32_e32 v80, v82
	v_permlane32_swap_b32_e32 v81, v83
	v_permlane32_swap_b32_e32 v90, v92
	v_permlane32_swap_b32_e32 v91, v93
	ds_read_b64_tr_b16 v[94:95], v206 offset:0x4000
	ds_read_b64_tr_b16 v[96:97], v206 offset:0x4800
	ds_read_b64_tr_b16 v[98:99], v206 offset:0x5000
	ds_read_b64_tr_b16 v[100:101], v206 offset:0x5800
	ds_read_b64_tr_b16 v[102:103], v206 offset:0x6000
	ds_read_b64_tr_b16 v[104:105], v206 offset:0x6800
	ds_read_b64_tr_b16 v[106:107], v206 offset:0x7000
	ds_read_b64_tr_b16 v[108:109], v206 offset:0x7800
	s_waitcnt lgkmcnt(0)
; #define SBAR() __builtin_amdgcn_sched_barrier(0)
; __device__ __forceinline__ int crow(int r, int hi) { return (r & 3) + 8 * (r >> 2) + 4 * hi; }
; #define NOP_() do { } while (0)
; template <bool PARTIAL, bool FIXED> ...
;     ...
;   HALF_A(2, 1, do { if (mask_last) { asm volatile("; masked tail tile" ::: "memory"); const float NEG = -INFINITY; \
;       _Pragma("unroll") for (int r = 8; r < 16; ++r) pA0[r] = NEG; _Pragma("unroll") for (int r = 0; r < 16; ++r) pA1[r] = NEG; } } while (0), NOP_(), NOP_());
;     ...
;   SBAR(); finishSM(pA0, pA1, alA, l_reg, pa0, pa1, pa2, pa3); SBAR();
;   pv_i<2 * 16384>(o, vbi, pa0, pa1, pa2, pa3);
;     ...
;   if (PARTIAL) {
;     if (wid < 2) { float* po = PO + (wid * QBLK) * 128;
; #pragma unroll
;       for (int r = 0; r < 16; ++r) { const int orow = crow(r, hi);
; #pragma unroll
;         for (int d0 = 0; d0 < 4; ++d0) po[orow * 128 + d0 * 32 + r32] = o[d0][r]; }
;       if (hi == 0) { PO[8192 + (wid * QBLK + r32) * 2] = m_reg; PO[8192 + (wid * QBLK + r32) * 2 + 1] = l_reg; } }
;     __syncthreads();
;     return;
;   }
;   if (hi == 0) li_l[r32] = l_reg; asm volatile("s_waitcnt lgkmcnt(0)" ::: "memory");
	s_nop 0
	v_mfma_f32_32x32x16_bf16 v[0:15], v[72:75], v[94:97], v[0:15]
	ds_read_b64_tr_b16 v[94:95], v206 offset:0x4200
	ds_read_b64_tr_b16 v[96:97], v206 offset:0x4a00
	v_mfma_f32_32x32x16_bf16 v[0:15], v[76:79], v[98:101], v[0:15]
	ds_read_b64_tr_b16 v[98:99], v206 offset:0x5200
	ds_read_b64_tr_b16 v[100:101], v206 offset:0x5a00
	v_mfma_f32_32x32x16_bf16 v[0:15], v[80:83], v[102:105], v[0:15]
	ds_read_b64_tr_b16 v[102:103], v206 offset:0x6200
	ds_read_b64_tr_b16 v[104:105], v206 offset:0x6a00
	v_mfma_f32_32x32x16_bf16 v[0:15], v[90:93], v[106:109], v[0:15]
	ds_read_b64_tr_b16 v[106:107], v206 offset:0x7200
	ds_read_b64_tr_b16 v[108:109], v206 offset:0x7a00
	s_waitcnt lgkmcnt(0)
	v_mfma_f32_32x32x16_bf16 v[16:31], v[72:75], v[94:97], v[16:31]
	ds_read_b64_tr_b16 v[94:95], v206 offset:0x4400
	ds_read_b64_tr_b16 v[96:97], v206 offset:0x4c00
	v_mfma_f32_32x32x16_bf16 v[16:31], v[76:79], v[98:101], v[16:31]
	ds_read_b64_tr_b16 v[98:99], v206 offset:0x5400
	ds_read_b64_tr_b16 v[100:101], v206 offset:0x5c00
	v_mfma_f32_32x32x16_bf16 v[16:31], v[80:83], v[102:105], v[16:31]
	ds_read_b64_tr_b16 v[102:103], v206 offset:0x6400
	ds_read_b64_tr_b16 v[104:105], v206 offset:0x6c00
	v_mfma_f32_32x32x16_bf16 v[16:31], v[90:93], v[106:109], v[16:31]
	ds_read_b64_tr_b16 v[106:107], v206 offset:0x7400
	ds_read_b64_tr_b16 v[108:109], v206 offset:0x7c00
	s_waitcnt lgkmcnt(0)
	v_mfma_f32_32x32x16_bf16 v[32:47], v[72:75], v[94:97], v[32:47]
	ds_read_b64_tr_b16 v[94:95], v206 offset:0x4600
	ds_read_b64_tr_b16 v[96:97], v206 offset:0x4e00
	v_mfma_f32_32x32x16_bf16 v[32:47], v[76:79], v[98:101], v[32:47]
	ds_read_b64_tr_b16 v[98:99], v206 offset:0x5600
	ds_read_b64_tr_b16 v[100:101], v206 offset:0x5e00
	v_mfma_f32_32x32x16_bf16 v[32:47], v[80:83], v[102:105], v[32:47]
	ds_read_b64_tr_b16 v[102:103], v206 offset:0x6600
	ds_read_b64_tr_b16 v[104:105], v206 offset:0x6e00
	v_mfma_f32_32x32x16_bf16 v[32:47], v[90:93], v[106:109], v[32:47]
	ds_read_b64_tr_b16 v[106:107], v206 offset:0x7600
	ds_read_b64_tr_b16 v[108:109], v206 offset:0x7e00
	s_waitcnt lgkmcnt(0)
	v_mfma_f32_32x32x16_bf16 v[48:63], v[72:75], v[94:97], v[48:63]
	v_exp_f32_e32 v64, v64
	v_exp_f32_e32 v65, v65
	v_exp_f32_e32 v66, v66
	v_exp_f32_e32 v67, v67
	v_exp_f32_e32 v68, v68
	v_exp_f32_e32 v69, v69
	v_exp_f32_e32 v70, v70
	v_mfma_f32_32x32x16_bf16 v[48:63], v[76:79], v[98:101], v[48:63]
	v_exp_f32_e32 v71, v71
	v_mfma_f32_32x32x16_bf16 v[48:63], v[80:83], v[102:105], v[48:63]
	v_mfma_f32_32x32x16_bf16 v[48:63], v[90:93], v[106:109], v[48:63]
	v_add_f32_e32 v72, 0, v64
	v_add_f32_e32 v72, v65, v72
	v_add_f32_e32 v72, v66, v72
	v_add_f32_e32 v72, v67, v72
	v_add_f32_e32 v72, v68, v72
	v_add_f32_e32 v72, v69, v72
	v_add_f32_e32 v72, v70, v72
	v_add_f32_e32 v72, v71, v72
	v_add_f32_e32 v85, 0, v72
	v_mov_b32_e32 v87, v85
	s_nop 1
	v_permlane32_swap_b32_e32 v85, v87
	v_cvt_pk_bf16_f32 v64, v64, v65
	v_cvt_pk_bf16_f32 v65, v66, v67
	v_cvt_pk_bf16_f32 v66, v68, v69
	v_cvt_pk_bf16_f32 v67, v70, v71
	v_cvt_pk_bf16_f32 v68, v129, v129
	v_cvt_pk_bf16_f32 v69, v129, v129
	v_cvt_pk_bf16_f32 v70, v129, v129
	v_cvt_pk_bf16_f32 v71, v129, v129
	v_cvt_pk_bf16_f32 v72, v129, v129
	v_cvt_pk_bf16_f32 v73, v129, v129
	v_cvt_pk_bf16_f32 v74, v129, v129
	v_cvt_pk_bf16_f32 v75, v129, v129
	v_cvt_pk_bf16_f32 v76, v129, v129
	v_cvt_pk_bf16_f32 v77, v129, v129
	v_cvt_pk_bf16_f32 v78, v129, v129
	v_cvt_pk_bf16_f32 v79, v129, v129
	s_nop 0
	v_permlane32_swap_b32_e32 v64, v66
	v_permlane32_swap_b32_e32 v65, v67
	v_permlane32_swap_b32_e32 v68, v70
	v_permlane32_swap_b32_e32 v69, v71
	v_permlane32_swap_b32_e32 v72, v74
	v_permlane32_swap_b32_e32 v73, v75
	v_permlane32_swap_b32_e32 v76, v78
	v_permlane32_swap_b32_e32 v77, v79
	ds_read_b64_tr_b16 v[80:81], v206 offset:0x8000
	ds_read_b64_tr_b16 v[82:83], v206 offset:0x8800
	ds_read_b64_tr_b16 v[90:91], v206 offset:0x9000
	ds_read_b64_tr_b16 v[92:93], v206 offset:0x9800
	ds_read_b64_tr_b16 v[94:95], v206 offset:0xa000
	ds_read_b64_tr_b16 v[96:97], v206 offset:0xa800
	ds_read_b64_tr_b16 v[98:99], v206 offset:0xb000
	ds_read_b64_tr_b16 v[100:101], v206 offset:0xb800
	s_waitcnt lgkmcnt(0)
	s_nop 0
	v_mfma_f32_32x32x16_bf16 v[0:15], v[64:67], v[80:83], v[0:15]
	ds_read_b64_tr_b16 v[80:81], v206 offset:0x8200
	ds_read_b64_tr_b16 v[82:83], v206 offset:0x8a00
	v_mfma_f32_32x32x16_bf16 v[0:15], v[68:71], v[90:93], v[0:15]
	ds_read_b64_tr_b16 v[90:91], v206 offset:0x9200
	ds_read_b64_tr_b16 v[92:93], v206 offset:0x9a00
	v_mfma_f32_32x32x16_bf16 v[0:15], v[72:75], v[94:97], v[0:15]
	ds_read_b64_tr_b16 v[94:95], v206 offset:0xa200
	ds_read_b64_tr_b16 v[96:97], v206 offset:0xaa00
	v_mfma_f32_32x32x16_bf16 v[0:15], v[76:79], v[98:101], v[0:15]
	ds_read_b64_tr_b16 v[98:99], v206 offset:0xb200
	ds_read_b64_tr_b16 v[100:101], v206 offset:0xba00
	s_waitcnt lgkmcnt(0)
	v_mfma_f32_32x32x16_bf16 v[16:31], v[64:67], v[80:83], v[16:31]
	ds_read_b64_tr_b16 v[80:81], v206 offset:0x8400
	ds_read_b64_tr_b16 v[82:83], v206 offset:0x8c00
	v_mfma_f32_32x32x16_bf16 v[16:31], v[68:71], v[90:93], v[16:31]
	ds_read_b64_tr_b16 v[90:91], v206 offset:0x9400
	ds_read_b64_tr_b16 v[92:93], v206 offset:0x9c00
	v_mfma_f32_32x32x16_bf16 v[16:31], v[72:75], v[94:97], v[16:31]
	ds_read_b64_tr_b16 v[94:95], v206 offset:0xa400
	ds_read_b64_tr_b16 v[96:97], v206 offset:0xac00
	v_mfma_f32_32x32x16_bf16 v[16:31], v[76:79], v[98:101], v[16:31]
	ds_read_b64_tr_b16 v[98:99], v206 offset:0xb400
	ds_read_b64_tr_b16 v[100:101], v206 offset:0xbc00
	s_waitcnt lgkmcnt(0)
	v_mfma_f32_32x32x16_bf16 v[32:47], v[64:67], v[80:83], v[32:47]
	ds_read_b64_tr_b16 v[80:81], v206 offset:0x8600
	ds_read_b64_tr_b16 v[82:83], v206 offset:0x8e00
	v_mfma_f32_32x32x16_bf16 v[32:47], v[68:71], v[90:93], v[32:47]
	ds_read_b64_tr_b16 v[90:91], v206 offset:0x9600
	ds_read_b64_tr_b16 v[92:93], v206 offset:0x9e00
	v_mfma_f32_32x32x16_bf16 v[32:47], v[72:75], v[94:97], v[32:47]
	ds_read_b64_tr_b16 v[94:95], v206 offset:0xa600
	ds_read_b64_tr_b16 v[96:97], v206 offset:0xae00
	v_mfma_f32_32x32x16_bf16 v[32:47], v[76:79], v[98:101], v[32:47]
	ds_read_b64_tr_b16 v[98:99], v206 offset:0xb600
	ds_read_b64_tr_b16 v[100:101], v206 offset:0xbe00
	s_waitcnt lgkmcnt(0)
	v_mfma_f32_32x32x16_bf16 v[48:63], v[64:67], v[80:83], v[48:63]
	v_cmp_gt_u32_e32 vcc, 32, v190
	v_mfma_f32_32x32x16_bf16 v[48:63], v[68:71], v[90:93], v[48:63]
	v_mfma_f32_32x32x16_bf16 v[48:63], v[72:75], v[94:97], v[48:63]
	v_mfma_f32_32x32x16_bf16 v[48:63], v[76:79], v[98:101], v[48:63]
	s_and_saveexec_b64 s[28:29], vcc
	s_cbranch_execz .LBB0_309
	v_add_f32_e32 v64, v128, v218
	v_add_f32_e32 v66, v215, v64
	v_pk_add_f32 v[64:65], v[84:85], v[86:87]
	v_lshl_add_u32 v67, v192, 2, v88
	v_add_f32_e32 v64, v66, v64
	v_add_f32_e32 v64, v64, v65
	ds_write_b32 v67, v64
	s_branch .LBB0_309
